# OUT and DOWN GEMM k-loops also rewritten with 16x16x32 bf16 MFMA (f32 acc); all four GEMMs now use the new loop
# speedup vs baseline: 1.0425x; 1.0222x over previous
.LBB0_923:
	s_ashr_i32 s2, s4, 31
	s_lshr_b32 s2, s2, 26
	s_add_i32 s2, s4, s2
	s_ashr_i32 s3, s2, 6
	s_lshl_b32 s3, s3, 3
	s_sub_i32 s8, s25, s3
	s_min_i32 s8, s8, 8
	s_abs_i32 s9, s8
	v_cvt_f32_u32_e32 v0, s9
	s_sub_i32 s12, 0, s9
	s_andn2_b32 s2, s2, 63
	s_sub_i32 s10, s4, s2
	v_rcp_iflag_f32_e32 v0, v0
	s_abs_i32 s2, s10
	s_xor_b32 s11, s10, s8
	s_ashr_i32 s11, s11, 31
	v_mul_f32_e32 v0, 0x4f7ffffe, v0
	v_cvt_u32_f32_e32 v0, v0
	v_mov_b32_e32 v181, v179
	v_readfirstlane_b32 s13, v0
	s_mul_i32 s12, s12, s13
	s_mul_hi_u32 s12, s13, s12
	s_add_i32 s13, s13, s12
	s_mul_hi_u32 s12, s2, s13
	s_mul_i32 s13, s12, s9
	s_sub_i32 s2, s2, s13
	s_add_i32 s14, s12, 1
	s_sub_i32 s13, s2, s9
	s_cmp_ge_u32 s2, s9
	s_cselect_b32 s12, s14, s12
	s_cselect_b32 s2, s13, s2
	s_add_i32 s13, s12, 1
	s_cmp_ge_u32 s2, s9
	s_cselect_b32 s2, s13, s12
	s_xor_b32 s2, s2, s11
	s_sub_i32 s2, s2, s11
	s_mul_i32 s8, s8, s2
	s_add_i32 s3, s3, s7
	s_sub_i32 s8, s10, s8
	v_ashrrev_i32_e32 v237, 6, v181
	s_add_i32 s8, s3, s8
	v_lshlrev_b32_e32 v0, 1, v237
	v_lshl_add_u32 v0, s8, 3, v0
	v_ashrrev_i32_e32 v1, 31, v0
	v_bfe_u32 v183, v181, 5, 1
	v_lshlrev_b64 v[0:1], 16, v[0:1]
	v_and_b32_e32 v238, 31, v181
	v_lshl_add_u64 v[0:1], s[64:65], 0, v[0:1]
	v_lshlrev_b32_e32 v176, 9, v183
	s_ashr_i32 s3, s2, 31
	v_lshl_add_u64 v[0:1], v[0:1], 0, v[176:177]
	v_lshlrev_b32_e32 v176, 4, v238
	v_ashrrev_i32_e32 v40, 2, v181
	s_lshl_b64 s[10:11], s[2:3], 18
	v_lshl_add_u64 v[184:185], v[0:1], 0, v[176:177]
	s_add_u32 s10, s5, s10
	v_lshlrev_b32_e32 v0, 5, v40
	s_addc_u32 s11, s6, s11
	v_ashrrev_i32_e32 v1, 31, v0
	v_lshlrev_b32_e32 v2, 4, v181
	v_lshl_add_u64 v[0:1], v[0:1], 1, s[10:11]
	v_and_b32_e32 v176, 48, v2
	v_lshl_add_u64 v[186:187], v[0:1], 0, v[176:177]
	s_movk_i32 s3, 0x2000
	v_add_co_u32_e32 v36, vcc, s3, v186
	v_mul_u32_u24_e32 v38, 40, v238
	s_nop 0
	v_addc_co_u32_e32 v37, vcc, 0, v187, vcc
	v_lshlrev_b32_e32 v39, 4, v183
	v_lshl_add_u32 v240, v38, 1, v39
	v_add_co_u32_e32 v38, vcc, s41, v184
	s_movk_i32 s9, 0x50
	s_nop 0
	v_addc_co_u32_e32 v39, vcc, 0, v185, vcc
	v_and_b32_e32 v239, 63, v181
	v_mov_b32_e32 v176, 0x800
	v_lshl_add_u64 v[188:189], v[186:187], 0, v[176:177]
	v_bfe_u32 v247, v181, 4, 1
	v_lshlrev_b32_e32 v176, 9, v183
	v_lshl_add_u32 v176, v247, 8, v176
	v_lshl_add_u64 v[184:185], v[184:185], 0, v[176:177]
	v_mov_b32_e32 v176, s41
	v_lshl_add_u64 v[186:187], v[184:185], 0, v[176:177]
	v_lshrrev_b32_e32 v241, 2, v181
	v_bfe_u32 v247, v181, 4, 2
	v_lshlrev_b32_e32 v247, 1, v247
	v_mov_b32_e32 v176, 0x78
	v_lshrrev_b32_e32 v247, v247, v176
	v_and_b32_e32 v247, 3, v247
	v_and_b32_e32 v246, 3, v181
	v_xor_b32_e32 v247, v247, v246
	v_lshlrev_b32_e32 v247, 4, v247
	v_lshl_add_u32 v241, v241, 6, v247
	v_bfe_u32 v247, v181, 2, 2
	v_lshlrev_b32_e32 v247, 1, v247
	v_lshrrev_b32_e32 v247, v247, v176
	v_and_b32_e32 v247, 3, v247
	v_bfe_u32 v246, v181, 4, 2
	v_xor_b32_e32 v247, v247, v246
	v_lshlrev_b32_e32 v247, 4, v247
	v_and_b32_e32 v246, 15, v181
	v_lshl_add_u32 v246, v246, 6, v247
	s_mov_b32 s96, 0
	v_lshl_add_u64 v[166:167], v[188:189], 0, s[96:97]
	global_load_dwordx4 v[160:163], v[166:167], off offset:-2048
	global_load_dwordx4 v[164:167], v[166:167], off offset:2048
	v_lshl_add_u64 v[248:249], v[184:185], 0, s[96:97]
	v_lshl_add_u64 v[250:251], v[186:187], 0, s[96:97]
	global_load_dwordx4 v[128:131], v[248:249], off
	global_load_dwordx4 v[132:135], v[248:249], off offset:256
	global_load_dwordx4 v[136:139], v[250:251], off
	global_load_dwordx4 v[140:143], v[250:251], off offset:256
	s_movk_i32 s96, 0x2000
	v_lshl_add_u64 v[174:175], v[188:189], 0, s[96:97]
	global_load_dwordx4 v[168:171], v[174:175], off offset:-2048
	global_load_dwordx4 v[172:175], v[174:175], off offset:2048
	s_movk_i32 s96, 0x800
	v_lshl_add_u64 v[248:249], v[184:185], 0, s[96:97]
	v_lshl_add_u64 v[250:251], v[186:187], 0, s[96:97]
	global_load_dwordx4 v[144:147], v[248:249], off
	global_load_dwordx4 v[148:151], v[248:249], off offset:256
	global_load_dwordx4 v[152:155], v[250:251], off
	global_load_dwordx4 v[156:159], v[250:251], off offset:256
	v_mov_b32_e32 v0, 0
	v_mov_b32_e32 v1, 0
	v_mov_b32_e32 v2, 0
	v_mov_b32_e32 v3, 0
	v_mov_b32_e32 v4, 0
	v_mov_b32_e32 v5, 0
	v_mov_b32_e32 v6, 0
	v_mov_b32_e32 v7, 0
	v_mov_b32_e32 v8, 0
	v_mov_b32_e32 v9, 0
	v_mov_b32_e32 v10, 0
	v_mov_b32_e32 v11, 0
	v_mov_b32_e32 v12, 0
	v_mov_b32_e32 v13, 0
	v_mov_b32_e32 v14, 0
	v_mov_b32_e32 v15, 0
	v_mov_b32_e32 v16, 0
	v_mov_b32_e32 v17, 0
	v_mov_b32_e32 v18, 0
	v_mov_b32_e32 v19, 0
	v_mov_b32_e32 v20, 0
	v_mov_b32_e32 v21, 0
	v_mov_b32_e32 v22, 0
	v_mov_b32_e32 v23, 0
	v_mov_b32_e32 v24, 0
	v_mov_b32_e32 v25, 0
	v_mov_b32_e32 v26, 0
	v_mov_b32_e32 v27, 0
	v_mov_b32_e32 v28, 0
	v_mov_b32_e32 v29, 0
	v_mov_b32_e32 v30, 0
	v_mov_b32_e32 v31, 0
	v_mov_b32_e32 v32, 0
	v_mov_b32_e32 v33, 0
	v_mov_b32_e32 v34, 0
	v_mov_b32_e32 v35, 0
	v_mov_b32_e32 v36, 0
	v_mov_b32_e32 v37, 0
	v_mov_b32_e32 v38, 0
	v_mov_b32_e32 v39, 0
	v_mov_b32_e32 v40, 0
	v_mov_b32_e32 v41, 0
	v_mov_b32_e32 v42, 0
	v_mov_b32_e32 v43, 0
	v_mov_b32_e32 v44, 0
	v_mov_b32_e32 v45, 0
	v_mov_b32_e32 v46, 0
	v_mov_b32_e32 v47, 0
	v_mov_b32_e32 v48, 0
	v_mov_b32_e32 v49, 0
	v_mov_b32_e32 v50, 0
	v_mov_b32_e32 v51, 0
	v_mov_b32_e32 v52, 0
	v_mov_b32_e32 v53, 0
	v_mov_b32_e32 v54, 0
	v_mov_b32_e32 v55, 0
	v_mov_b32_e32 v56, 0
	v_mov_b32_e32 v57, 0
	v_mov_b32_e32 v58, 0
	v_mov_b32_e32 v59, 0
	v_mov_b32_e32 v60, 0
	v_mov_b32_e32 v61, 0
	v_mov_b32_e32 v62, 0
	v_mov_b32_e32 v63, 0
	v_mov_b32_e32 v64, 0
	v_mov_b32_e32 v65, 0
	v_mov_b32_e32 v66, 0
	v_mov_b32_e32 v67, 0
	v_mov_b32_e32 v68, 0
	v_mov_b32_e32 v69, 0
	v_mov_b32_e32 v70, 0
	v_mov_b32_e32 v71, 0
	v_mov_b32_e32 v72, 0
	v_mov_b32_e32 v73, 0
	v_mov_b32_e32 v74, 0
	v_mov_b32_e32 v75, 0
	v_mov_b32_e32 v76, 0
	v_mov_b32_e32 v77, 0
	v_mov_b32_e32 v78, 0
	v_mov_b32_e32 v79, 0
	v_mov_b32_e32 v80, 0
	v_mov_b32_e32 v81, 0
	v_mov_b32_e32 v82, 0
	v_mov_b32_e32 v83, 0
	v_mov_b32_e32 v84, 0
	v_mov_b32_e32 v85, 0
	v_mov_b32_e32 v86, 0
	v_mov_b32_e32 v87, 0
	v_mov_b32_e32 v88, 0
	v_mov_b32_e32 v89, 0
	v_mov_b32_e32 v90, 0
	v_mov_b32_e32 v91, 0
	v_mov_b32_e32 v92, 0
	v_mov_b32_e32 v93, 0
	v_mov_b32_e32 v94, 0
	v_mov_b32_e32 v95, 0
	v_mov_b32_e32 v96, 0
	v_mov_b32_e32 v97, 0
	v_mov_b32_e32 v98, 0
	v_mov_b32_e32 v99, 0
	v_mov_b32_e32 v100, 0
	v_mov_b32_e32 v101, 0
	v_mov_b32_e32 v102, 0
	v_mov_b32_e32 v103, 0
	v_mov_b32_e32 v104, 0
	v_mov_b32_e32 v105, 0
	v_mov_b32_e32 v106, 0
	v_mov_b32_e32 v107, 0
	v_mov_b32_e32 v108, 0
	v_mov_b32_e32 v109, 0
	v_mov_b32_e32 v110, 0
	v_mov_b32_e32 v111, 0
	v_mov_b32_e32 v112, 0
	v_mov_b32_e32 v113, 0
	v_mov_b32_e32 v114, 0
	v_mov_b32_e32 v115, 0
	v_mov_b32_e32 v116, 0
	v_mov_b32_e32 v117, 0
	v_mov_b32_e32 v118, 0
	v_mov_b32_e32 v119, 0
	v_mov_b32_e32 v120, 0
	v_mov_b32_e32 v121, 0
	v_mov_b32_e32 v122, 0
	v_mov_b32_e32 v123, 0
	v_mov_b32_e32 v124, 0
	v_mov_b32_e32 v125, 0
	v_mov_b32_e32 v126, 0
	v_mov_b32_e32 v127, 0
	s_mov_b32 s3, 0
	s_waitcnt vmcnt(10)
	ds_write_b128 v241, v[160:163]
	ds_write_b128 v241, v[164:167] offset:4096
	s_waitcnt lgkmcnt(0)
	s_barrier
.Lg16_out_k:
	s_add_i32 s9, s3, 2
	s_min_u32 s10, s9, 30
	s_lshl_b32 s96, s10, 13
	v_lshl_add_u64 v[166:167], v[188:189], 0, s[96:97]
	global_load_dwordx4 v[160:163], v[166:167], off offset:-2048
	global_load_dwordx4 v[164:167], v[166:167], off offset:2048
	ds_read_b128 v[196:199], v246 offset:0
	ds_read_b128 v[200:203], v246 offset:1024
	ds_read_b128 v[204:207], v246 offset:2048
	ds_read_b128 v[242:245], v246 offset:3072
	s_lshl_b32 s96, s10, 11
	v_lshl_add_u64 v[248:249], v[184:185], 0, s[96:97]
	v_lshl_add_u64 v[250:251], v[186:187], 0, s[96:97]
	s_waitcnt vmcnt(8) lgkmcnt(3)
	v_mfma_f32_16x16x32_bf16 v[112:115], v[128:131], v[196:199], v[112:115]
	v_mfma_f32_16x16x32_bf16 v[120:123], v[132:135], v[196:199], v[120:123]
	v_mfma_f32_16x16x32_bf16 v[48:51], v[136:139], v[196:199], v[48:51]
	v_mfma_f32_16x16x32_bf16 v[56:59], v[140:143], v[196:199], v[56:59]
	ds_read_b128 v[196:199], v246 offset:4096
	s_waitcnt lgkmcnt(3)
	v_mfma_f32_16x16x32_bf16 v[116:119], v[128:131], v[200:203], v[116:119]
	v_mfma_f32_16x16x32_bf16 v[124:127], v[132:135], v[200:203], v[124:127]
	v_mfma_f32_16x16x32_bf16 v[52:55], v[136:139], v[200:203], v[52:55]
	v_mfma_f32_16x16x32_bf16 v[60:63], v[140:143], v[200:203], v[60:63]
	ds_read_b128 v[200:203], v246 offset:5120
	s_waitcnt lgkmcnt(3)
	v_mfma_f32_16x16x32_bf16 v[96:99], v[128:131], v[204:207], v[96:99]
	v_mfma_f32_16x16x32_bf16 v[104:107], v[132:135], v[204:207], v[104:107]
	v_mfma_f32_16x16x32_bf16 v[32:35], v[136:139], v[204:207], v[32:35]
	v_mfma_f32_16x16x32_bf16 v[40:43], v[140:143], v[204:207], v[40:43]
	ds_read_b128 v[204:207], v246 offset:6144
	s_waitcnt lgkmcnt(3)
	v_mfma_f32_16x16x32_bf16 v[100:103], v[128:131], v[242:245], v[100:103]
	v_mfma_f32_16x16x32_bf16 v[108:111], v[132:135], v[242:245], v[108:111]
	v_mfma_f32_16x16x32_bf16 v[36:39], v[136:139], v[242:245], v[36:39]
	v_mfma_f32_16x16x32_bf16 v[44:47], v[140:143], v[242:245], v[44:47]
	ds_read_b128 v[242:245], v246 offset:7168
	s_waitcnt vmcnt(6)
	ds_write_b128 v241, v[168:171] offset:8192
	ds_write_b128 v241, v[172:175] offset:12288
	s_waitcnt lgkmcnt(5)
	v_mfma_f32_16x16x32_bf16 v[80:83], v[128:131], v[196:199], v[80:83]
	v_mfma_f32_16x16x32_bf16 v[88:91], v[132:135], v[196:199], v[88:91]
	v_mfma_f32_16x16x32_bf16 v[16:19], v[136:139], v[196:199], v[16:19]
	v_mfma_f32_16x16x32_bf16 v[24:27], v[140:143], v[196:199], v[24:27]
	s_waitcnt lgkmcnt(4)
	v_mfma_f32_16x16x32_bf16 v[84:87], v[128:131], v[200:203], v[84:87]
	v_mfma_f32_16x16x32_bf16 v[92:95], v[132:135], v[200:203], v[92:95]
	v_mfma_f32_16x16x32_bf16 v[20:23], v[136:139], v[200:203], v[20:23]
	v_mfma_f32_16x16x32_bf16 v[28:31], v[140:143], v[200:203], v[28:31]
	s_waitcnt lgkmcnt(3)
	v_mfma_f32_16x16x32_bf16 v[64:67], v[128:131], v[204:207], v[64:67]
	v_mfma_f32_16x16x32_bf16 v[72:75], v[132:135], v[204:207], v[72:75]
	v_mfma_f32_16x16x32_bf16 v[0:3], v[136:139], v[204:207], v[0:3]
	v_mfma_f32_16x16x32_bf16 v[8:11], v[140:143], v[204:207], v[8:11]
	s_waitcnt lgkmcnt(2)
	v_mfma_f32_16x16x32_bf16 v[68:71], v[128:131], v[242:245], v[68:71]
	v_mfma_f32_16x16x32_bf16 v[76:79], v[132:135], v[242:245], v[76:79]
	v_mfma_f32_16x16x32_bf16 v[4:7], v[136:139], v[242:245], v[4:7]
	v_mfma_f32_16x16x32_bf16 v[12:15], v[140:143], v[242:245], v[12:15]
	global_load_dwordx4 v[128:131], v[248:249], off
	global_load_dwordx4 v[132:135], v[248:249], off offset:256
	global_load_dwordx4 v[136:139], v[250:251], off
	global_load_dwordx4 v[140:143], v[250:251], off offset:256
	s_waitcnt lgkmcnt(0)
	s_barrier
	s_add_i32 s9, s3, 3
	s_min_u32 s10, s9, 31
	s_lshl_b32 s96, s10, 13
	v_lshl_add_u64 v[174:175], v[188:189], 0, s[96:97]
	global_load_dwordx4 v[168:171], v[174:175], off offset:-2048
	global_load_dwordx4 v[172:175], v[174:175], off offset:2048
	ds_read_b128 v[196:199], v246 offset:8192
	ds_read_b128 v[200:203], v246 offset:9216
	ds_read_b128 v[204:207], v246 offset:10240
	ds_read_b128 v[242:245], v246 offset:11264
	s_lshl_b32 s96, s10, 11
	v_lshl_add_u64 v[248:249], v[184:185], 0, s[96:97]
	v_lshl_add_u64 v[250:251], v[186:187], 0, s[96:97]
	s_waitcnt vmcnt(8) lgkmcnt(3)
	v_mfma_f32_16x16x32_bf16 v[112:115], v[144:147], v[196:199], v[112:115]
	v_mfma_f32_16x16x32_bf16 v[120:123], v[148:151], v[196:199], v[120:123]
	v_mfma_f32_16x16x32_bf16 v[48:51], v[152:155], v[196:199], v[48:51]
	v_mfma_f32_16x16x32_bf16 v[56:59], v[156:159], v[196:199], v[56:59]
	ds_read_b128 v[196:199], v246 offset:12288
	s_waitcnt lgkmcnt(3)
	v_mfma_f32_16x16x32_bf16 v[116:119], v[144:147], v[200:203], v[116:119]
	v_mfma_f32_16x16x32_bf16 v[124:127], v[148:151], v[200:203], v[124:127]
	v_mfma_f32_16x16x32_bf16 v[52:55], v[152:155], v[200:203], v[52:55]
	v_mfma_f32_16x16x32_bf16 v[60:63], v[156:159], v[200:203], v[60:63]
	ds_read_b128 v[200:203], v246 offset:13312
	s_waitcnt lgkmcnt(3)
	v_mfma_f32_16x16x32_bf16 v[96:99], v[144:147], v[204:207], v[96:99]
	v_mfma_f32_16x16x32_bf16 v[104:107], v[148:151], v[204:207], v[104:107]
	v_mfma_f32_16x16x32_bf16 v[32:35], v[152:155], v[204:207], v[32:35]
	v_mfma_f32_16x16x32_bf16 v[40:43], v[156:159], v[204:207], v[40:43]
	ds_read_b128 v[204:207], v246 offset:14336
	s_waitcnt lgkmcnt(3)
	v_mfma_f32_16x16x32_bf16 v[100:103], v[144:147], v[242:245], v[100:103]
	v_mfma_f32_16x16x32_bf16 v[108:111], v[148:151], v[242:245], v[108:111]
	v_mfma_f32_16x16x32_bf16 v[36:39], v[152:155], v[242:245], v[36:39]
	v_mfma_f32_16x16x32_bf16 v[44:47], v[156:159], v[242:245], v[44:47]
	ds_read_b128 v[242:245], v246 offset:15360
	s_waitcnt vmcnt(6)
	ds_write_b128 v241, v[160:163] offset:0
	ds_write_b128 v241, v[164:167] offset:4096
	s_waitcnt lgkmcnt(5)
	v_mfma_f32_16x16x32_bf16 v[80:83], v[144:147], v[196:199], v[80:83]
	v_mfma_f32_16x16x32_bf16 v[88:91], v[148:151], v[196:199], v[88:91]
	v_mfma_f32_16x16x32_bf16 v[16:19], v[152:155], v[196:199], v[16:19]
	v_mfma_f32_16x16x32_bf16 v[24:27], v[156:159], v[196:199], v[24:27]
	s_waitcnt lgkmcnt(4)
	v_mfma_f32_16x16x32_bf16 v[84:87], v[144:147], v[200:203], v[84:87]
	v_mfma_f32_16x16x32_bf16 v[92:95], v[148:151], v[200:203], v[92:95]
	v_mfma_f32_16x16x32_bf16 v[20:23], v[152:155], v[200:203], v[20:23]
	v_mfma_f32_16x16x32_bf16 v[28:31], v[156:159], v[200:203], v[28:31]
	s_waitcnt lgkmcnt(3)
	v_mfma_f32_16x16x32_bf16 v[64:67], v[144:147], v[204:207], v[64:67]
	v_mfma_f32_16x16x32_bf16 v[72:75], v[148:151], v[204:207], v[72:75]
	v_mfma_f32_16x16x32_bf16 v[0:3], v[152:155], v[204:207], v[0:3]
	v_mfma_f32_16x16x32_bf16 v[8:11], v[156:159], v[204:207], v[8:11]
	s_waitcnt lgkmcnt(2)
	v_mfma_f32_16x16x32_bf16 v[68:71], v[144:147], v[242:245], v[68:71]
	v_mfma_f32_16x16x32_bf16 v[76:79], v[148:151], v[242:245], v[76:79]
	v_mfma_f32_16x16x32_bf16 v[4:7], v[152:155], v[242:245], v[4:7]
	v_mfma_f32_16x16x32_bf16 v[12:15], v[156:159], v[242:245], v[12:15]
	global_load_dwordx4 v[144:147], v[248:249], off
	global_load_dwordx4 v[148:151], v[248:249], off offset:256
	global_load_dwordx4 v[152:155], v[250:251], off
	global_load_dwordx4 v[156:159], v[250:251], off offset:256
	s_add_i32 s3, s3, 2
	s_cmp_lt_u32 s3, 32
	s_waitcnt lgkmcnt(0)
	s_barrier
	s_cbranch_scc1 .Lg16_out_k
	s_nop 7
	v_permlane16_swap_b32_e32 v112, v116
	v_permlane16_swap_b32_e32 v113, v117
	v_permlane16_swap_b32_e32 v114, v118
	v_permlane16_swap_b32_e32 v115, v119
	v_permlane16_swap_b32_e32 v120, v124
	v_permlane16_swap_b32_e32 v121, v125
	v_permlane16_swap_b32_e32 v122, v126
	v_permlane16_swap_b32_e32 v123, v127
	v_permlane16_swap_b32_e32 v96, v100
	v_permlane16_swap_b32_e32 v97, v101
	v_permlane16_swap_b32_e32 v98, v102
	v_permlane16_swap_b32_e32 v99, v103
	v_permlane16_swap_b32_e32 v104, v108
	v_permlane16_swap_b32_e32 v105, v109
	v_permlane16_swap_b32_e32 v106, v110
	v_permlane16_swap_b32_e32 v107, v111
	v_permlane16_swap_b32_e32 v80, v84
	v_permlane16_swap_b32_e32 v81, v85
	v_permlane16_swap_b32_e32 v82, v86
	v_permlane16_swap_b32_e32 v83, v87
	v_permlane16_swap_b32_e32 v88, v92
	v_permlane16_swap_b32_e32 v89, v93
	v_permlane16_swap_b32_e32 v90, v94
	v_permlane16_swap_b32_e32 v91, v95
	v_permlane16_swap_b32_e32 v64, v68
	v_permlane16_swap_b32_e32 v65, v69
	v_permlane16_swap_b32_e32 v66, v70
	v_permlane16_swap_b32_e32 v67, v71
	v_permlane16_swap_b32_e32 v72, v76
	v_permlane16_swap_b32_e32 v73, v77
	v_permlane16_swap_b32_e32 v74, v78
	v_permlane16_swap_b32_e32 v75, v79
	v_permlane16_swap_b32_e32 v48, v52
	v_permlane16_swap_b32_e32 v49, v53
	v_permlane16_swap_b32_e32 v50, v54
	v_permlane16_swap_b32_e32 v51, v55
	v_permlane16_swap_b32_e32 v56, v60
	v_permlane16_swap_b32_e32 v57, v61
	v_permlane16_swap_b32_e32 v58, v62
	v_permlane16_swap_b32_e32 v59, v63
	v_permlane16_swap_b32_e32 v32, v36
	v_permlane16_swap_b32_e32 v33, v37
	v_permlane16_swap_b32_e32 v34, v38
	v_permlane16_swap_b32_e32 v35, v39
	v_permlane16_swap_b32_e32 v40, v44
	v_permlane16_swap_b32_e32 v41, v45
	v_permlane16_swap_b32_e32 v42, v46
	v_permlane16_swap_b32_e32 v43, v47
	v_permlane16_swap_b32_e32 v16, v20
	v_permlane16_swap_b32_e32 v17, v21
	v_permlane16_swap_b32_e32 v18, v22
	v_permlane16_swap_b32_e32 v19, v23
	v_permlane16_swap_b32_e32 v24, v28
	v_permlane16_swap_b32_e32 v25, v29
	v_permlane16_swap_b32_e32 v26, v30
	v_permlane16_swap_b32_e32 v27, v31
	v_permlane16_swap_b32_e32 v0, v4
	v_permlane16_swap_b32_e32 v1, v5
	v_permlane16_swap_b32_e32 v2, v6
	v_permlane16_swap_b32_e32 v3, v7
	v_permlane16_swap_b32_e32 v8, v12
	v_permlane16_swap_b32_e32 v9, v13
	v_permlane16_swap_b32_e32 v10, v14
	v_permlane16_swap_b32_e32 v11, v15
	v_permlane32_swap_b32_e32 v112, v116
	v_permlane32_swap_b32_e32 v113, v117
	v_permlane32_swap_b32_e32 v114, v118
	v_permlane32_swap_b32_e32 v115, v119
	v_permlane32_swap_b32_e32 v120, v124
	v_permlane32_swap_b32_e32 v121, v125
	v_permlane32_swap_b32_e32 v122, v126
	v_permlane32_swap_b32_e32 v123, v127
	v_permlane32_swap_b32_e32 v96, v100
	v_permlane32_swap_b32_e32 v97, v101
	v_permlane32_swap_b32_e32 v98, v102
	v_permlane32_swap_b32_e32 v99, v103
	v_permlane32_swap_b32_e32 v104, v108
	v_permlane32_swap_b32_e32 v105, v109
	v_permlane32_swap_b32_e32 v106, v110
	v_permlane32_swap_b32_e32 v107, v111
	v_permlane32_swap_b32_e32 v80, v84
	v_permlane32_swap_b32_e32 v81, v85
	v_permlane32_swap_b32_e32 v82, v86
	v_permlane32_swap_b32_e32 v83, v87
	v_permlane32_swap_b32_e32 v88, v92
	v_permlane32_swap_b32_e32 v89, v93
	v_permlane32_swap_b32_e32 v90, v94
	v_permlane32_swap_b32_e32 v91, v95
	v_permlane32_swap_b32_e32 v64, v68
	v_permlane32_swap_b32_e32 v65, v69
	v_permlane32_swap_b32_e32 v66, v70
	v_permlane32_swap_b32_e32 v67, v71
	v_permlane32_swap_b32_e32 v72, v76
	v_permlane32_swap_b32_e32 v73, v77
	v_permlane32_swap_b32_e32 v74, v78
	v_permlane32_swap_b32_e32 v75, v79
	v_permlane32_swap_b32_e32 v48, v52
	v_permlane32_swap_b32_e32 v49, v53
	v_permlane32_swap_b32_e32 v50, v54
	v_permlane32_swap_b32_e32 v51, v55
	v_permlane32_swap_b32_e32 v56, v60
	v_permlane32_swap_b32_e32 v57, v61
	v_permlane32_swap_b32_e32 v58, v62
	v_permlane32_swap_b32_e32 v59, v63
	v_permlane32_swap_b32_e32 v32, v36
	v_permlane32_swap_b32_e32 v33, v37
	v_permlane32_swap_b32_e32 v34, v38
	v_permlane32_swap_b32_e32 v35, v39
	v_permlane32_swap_b32_e32 v40, v44
	v_permlane32_swap_b32_e32 v41, v45
	v_permlane32_swap_b32_e32 v42, v46
	v_permlane32_swap_b32_e32 v43, v47
	v_permlane32_swap_b32_e32 v16, v20
	v_permlane32_swap_b32_e32 v17, v21
	v_permlane32_swap_b32_e32 v18, v22
	v_permlane32_swap_b32_e32 v19, v23
	v_permlane32_swap_b32_e32 v24, v28
	v_permlane32_swap_b32_e32 v25, v29
	v_permlane32_swap_b32_e32 v26, v30
	v_permlane32_swap_b32_e32 v27, v31
	v_permlane32_swap_b32_e32 v0, v4
	v_permlane32_swap_b32_e32 v1, v5
	v_permlane32_swap_b32_e32 v2, v6
	v_permlane32_swap_b32_e32 v3, v7
	v_permlane32_swap_b32_e32 v8, v12
	v_permlane32_swap_b32_e32 v9, v13
	v_permlane32_swap_b32_e32 v10, v14
	v_permlane32_swap_b32_e32 v11, v15
	s_waitcnt vmcnt(0)
	s_movk_i32 s3, 0x2400
	s_waitcnt vmcnt(6)
	v_lshlrev_b32_e32 v128, 2, v181
	s_waitcnt vmcnt(0)
	v_and_b32_e32 v133, 0xffffffc0, v181
	v_mul_lo_u32 v129, v237, s3
	v_lshlrev_b32_e32 v130, 2, v238
	v_and_b32_e32 v128, 60, v128
	v_lshl_add_u32 v176, s8, 8, v133
	v_mul_u32_u24_e32 v133, 0x110, v183
	v_or_b32_e32 v131, v129, v130
	v_lshl_or_b32 v132, v128, 2, v129
	v_lshl_or_b32 v128, s2, 7, v128
	v_lshlrev_b32_e32 v133, 2, v133
	v_lshrrev_b32_e32 v175, 4, v239
	s_movk_i32 s2, 0x110
	v_add_u32_e32 v147, v131, v133
	v_add3_u32 v148, v129, v133, v130
	v_mad_u32_u24 v146, v175, s2, v132
	v_readlane_b32 s2, v254, 39
	v_readlane_b32 s8, v253, 36
	v_add_u32_e32 v149, 0x800, v147
	v_add_u32_e32 v150, 0x800, v148
	v_add_u32_e32 v151, 0xa00, v148
	v_mov_b32_e32 v160, s2
	v_readlane_b32 s2, v254, 37
	v_readlane_b32 s9, v253, 37
	v_readlane_b32 s10, v253, 38
	v_readlane_b32 s11, v253, 39
	v_readlane_b32 s12, v253, 40
	v_readlane_b32 s13, v253, 41
	v_readlane_b32 s14, v253, 42
	v_readlane_b32 s15, v253, 43
	v_readlane_b32 s16, v253, 44
	v_readlane_b32 s17, v253, 45
	ds_write2_b32 v147, v112, v113 offset1:68
	ds_write2_b32 v148, v96, v97 offset0:32 offset1:100
	ds_write2_b32 v147, v114, v115 offset0:136 offset1:204
	ds_write2_b32 v148, v98, v99 offset0:168 offset1:236
	ds_write2_b32 v149, v116, v117 offset0:32 offset1:100
	ds_write2_b32 v150, v100, v101 offset0:64 offset1:132
	ds_write2_b32 v149, v118, v119 offset0:168 offset1:236
	ds_write2_b32 v151, v102, v103 offset0:72 offset1:140
	v_or_b32_e32 v102, v176, v175
	v_mov_b32_e32 v161, s2
	v_readlane_b32 s2, v254, 40
	v_readlane_b32 s18, v253, 46
	v_readlane_b32 s19, v253, 47
	v_readlane_b32 s20, v253, 48
	v_readlane_b32 s21, v253, 49
	v_readlane_b32 s22, v253, 50
	v_readlane_b32 s23, v253, 51
	s_mov_b64 s[8:9], s[16:17]
	v_cmp_gt_i32_e32 vcc, s39, v102
	v_add_u32_e32 v96, 0xffff8000, v102
	v_ashrrev_i32_e32 v97, 31, v102
	v_mov_b32_e32 v162, s2
	v_readlane_b32 s2, v254, 38
	s_mov_b64 s[10:11], s[18:19]
	v_cndmask_b32_e32 v97, 0, v97, vcc
	v_cndmask_b32_e32 v96, v96, v102, vcc
	v_mov_b32_e32 v163, s2
	v_mov_b32_e32 v164, s63
	v_mov_b32_e32 v165, s11
	v_mov_b32_e32 v166, s62
	v_mov_b32_e32 v167, s10
	v_min_i32_e32 v102, 0x8000, v102
	v_add_u32_e32 v152, 0x1000, v147
	v_add_u32_e32 v153, 0x1000, v148
	v_add_u32_e32 v154, 0x1200, v147
	v_add_u32_e32 v155, 0x1200, v148
	v_add_u32_e32 v156, 0x1800, v147
	v_add_u32_e32 v157, 0x1800, v148
	v_add_u32_e32 v158, 0x1a00, v147
	v_add_u32_e32 v159, 0x1c00, v148
	v_ashrrev_i32_e32 v129, 31, v128
	v_cndmask_b32_e32 v99, v160, v161, vcc
	v_cndmask_b32_e32 v98, v162, v163, vcc
	v_lshlrev_b64 v[96:97], 12, v[96:97]
	v_cndmask_b32_e32 v101, v164, v165, vcc
	v_cndmask_b32_e32 v100, v166, v167, vcc
	v_ashrrev_i32_e32 v102, 12, v102
	ds_write2_b32 v152, v120, v121 offset0:64 offset1:132
	ds_write2_b32 v153, v104, v105 offset0:96 offset1:164
	ds_write2_b32 v154, v122, v123 offset0:72 offset1:140
	ds_write2_b32 v155, v106, v107 offset0:104 offset1:172
	ds_write2_b32 v156, v124, v125 offset0:96 offset1:164
	ds_write2_b32 v157, v108, v109 offset0:128 offset1:196
	ds_write2_b32 v158, v126, v127 offset0:104 offset1:172
	ds_write2_b32 v159, v110, v111 offset0:8 offset1:76
	v_lshl_add_u64 v[98:99], v[98:99], 0, v[96:97]
	v_lshl_add_u64 v[100:101], v[100:101], 0, v[96:97]
	v_lshlrev_b64 v[96:97], 2, v[128:129]
	v_mul_hi_i32_i24_e32 v103, 0x6000, v102
	v_mul_i32_i24_e32 v102, 0x6000, v102
	s_waitcnt lgkmcnt(0)
	v_lshl_add_u64 v[98:99], v[98:99], 0, v[96:97]
	v_lshl_add_u64 v[102:103], s[0:1], 0, v[102:103]
	v_lshl_add_u64 v[102:103], v[102:103], 0, v[96:97]
	ds_read_b128 v[104:107], v146
	global_load_dwordx4 v[108:111], v[98:99], off
	global_load_dwordx4 v[112:115], v[102:103], off
	v_or_b32_e32 v168, 4, v175
	v_lshl_add_u64 v[100:101], v[100:101], 0, v[96:97]
	v_or_b32_e32 v169, 8, v175
	v_or_b32_e32 v170, 12, v175
	v_or_b32_e32 v171, 16, v175
	v_or_b32_e32 v172, 20, v175
	v_or_b32_e32 v173, 24, v175
	v_or_b32_e32 v174, 28, v175
	v_or_b32_e32 v181, v176, v174
	v_readlane_b32 s2, v254, 11
	s_add_i32 s4, s4, s2
	s_cmp_lt_i32 s4, s26
	s_mov_b64 s[12:13], s[20:21]
	s_mov_b64 s[14:15], s[22:23]
	s_waitcnt vmcnt(0) lgkmcnt(0)
	v_pk_fma_f32 v[104:105], v[104:105], v[112:113], v[108:109]
	v_pk_fma_f32 v[106:107], v[106:107], v[114:115], v[110:111]
	v_or_b32_e32 v110, v176, v168
	global_store_dwordx4 v[100:101], v[104:107], off
	v_cmp_gt_i32_e32 vcc, s39, v110
	s_nop 0
	v_ashrrev_i32_e32 v104, 31, v110
	v_add_u32_e32 v106, 0xffff8000, v110
	v_cndmask_b32_e32 v105, 0, v104, vcc
	v_cndmask_b32_e32 v104, v106, v110, vcc
	v_cndmask_b32_e32 v107, v160, v161, vcc
	v_cndmask_b32_e32 v106, v162, v163, vcc
	v_lshlrev_b64 v[104:105], 12, v[104:105]
	v_cndmask_b32_e32 v109, v164, v165, vcc
	v_cndmask_b32_e32 v108, v166, v167, vcc
	v_lshl_add_u64 v[106:107], v[106:107], 0, v[104:105]
	v_lshl_add_u64 v[104:105], v[108:109], 0, v[104:105]
	v_min_i32_e32 v108, 0x8000, v110
	v_ashrrev_i32_e32 v108, 12, v108
	v_mul_hi_i32_i24_e32 v109, 0x6000, v108
	v_mul_i32_i24_e32 v108, 0x6000, v108
	v_lshl_add_u64 v[106:107], v[106:107], 0, v[96:97]
	v_lshl_add_u64 v[108:109], s[0:1], 0, v[108:109]
	v_lshl_add_u64 v[108:109], v[108:109], 0, v[96:97]
	ds_read_b128 v[110:113], v146 offset:1088
	global_load_dwordx4 v[114:117], v[106:107], off
	global_load_dwordx4 v[118:121], v[108:109], off
	v_lshl_add_u64 v[104:105], v[104:105], 0, v[96:97]
	s_waitcnt vmcnt(0) lgkmcnt(0)
	v_pk_fma_f32 v[110:111], v[110:111], v[118:119], v[114:115]
	v_pk_fma_f32 v[112:113], v[112:113], v[120:121], v[116:117]
	v_or_b32_e32 v118, v176, v169
	global_store_dwordx4 v[104:105], v[110:113], off
	v_cmp_gt_i32_e32 vcc, s39, v118
	s_nop 0
	v_ashrrev_i32_e32 v110, 31, v118
	v_add_u32_e32 v112, 0xffff8000, v118
	v_cndmask_b32_e32 v111, 0, v110, vcc
	v_cndmask_b32_e32 v110, v112, v118, vcc
	v_cndmask_b32_e32 v113, v160, v161, vcc
	v_cndmask_b32_e32 v112, v162, v163, vcc
	v_lshlrev_b64 v[110:111], 12, v[110:111]
	v_lshl_add_u64 v[112:113], v[112:113], 0, v[110:111]
	v_cndmask_b32_e32 v115, v164, v165, vcc
	v_cndmask_b32_e32 v114, v166, v167, vcc
	v_lshl_add_u64 v[116:117], v[114:115], 0, v[110:111]
	v_lshl_add_u64 v[110:111], v[112:113], 0, v[96:97]
	v_min_i32_e32 v112, 0x8000, v118
	v_ashrrev_i32_e32 v112, 12, v112
	v_mul_hi_i32_i24_e32 v113, 0x6000, v112
	v_mul_i32_i24_e32 v112, 0x6000, v112
	v_lshl_add_u64 v[112:113], s[0:1], 0, v[112:113]
	v_lshl_add_u64 v[114:115], v[112:113], 0, v[96:97]
	v_lshl_add_u64 v[112:113], v[116:117], 0, v[96:97]
	ds_read_b128 v[116:119], v146 offset:2176
	global_load_dwordx4 v[120:123], v[110:111], off
	global_load_dwordx4 v[124:127], v[114:115], off
	s_waitcnt vmcnt(0) lgkmcnt(0)
	v_pk_fma_f32 v[116:117], v[116:117], v[124:125], v[120:121]
	v_pk_fma_f32 v[118:119], v[118:119], v[126:127], v[122:123]
	v_or_b32_e32 v124, v176, v170
	global_store_dwordx4 v[112:113], v[116:119], off
	v_cmp_gt_i32_e32 vcc, s39, v124
	s_nop 0
	v_ashrrev_i32_e32 v116, 31, v124
	v_add_u32_e32 v118, 0xffff8000, v124
	v_cndmask_b32_e32 v117, 0, v116, vcc
	v_cndmask_b32_e32 v116, v118, v124, vcc
	v_cndmask_b32_e32 v119, v160, v161, vcc
	v_cndmask_b32_e32 v118, v162, v163, vcc
	v_lshlrev_b64 v[116:117], 12, v[116:117]
	v_lshl_add_u64 v[118:119], v[118:119], 0, v[116:117]
	v_cndmask_b32_e32 v121, v164, v165, vcc
	v_cndmask_b32_e32 v120, v166, v167, vcc
	v_lshl_add_u64 v[122:123], v[120:121], 0, v[116:117]
	v_lshl_add_u64 v[116:117], v[118:119], 0, v[96:97]
	v_min_i32_e32 v118, 0x8000, v124
	v_ashrrev_i32_e32 v118, 12, v118
	v_mul_hi_i32_i24_e32 v119, 0x6000, v118
	v_mul_i32_i24_e32 v118, 0x6000, v118
	v_lshl_add_u64 v[118:119], s[0:1], 0, v[118:119]
	v_lshl_add_u64 v[120:121], v[118:119], 0, v[96:97]
	v_lshl_add_u64 v[118:119], v[122:123], 0, v[96:97]
	ds_read_b128 v[122:125], v146 offset:3264
	global_load_dwordx4 v[126:129], v[116:117], off
	global_load_dwordx4 v[130:133], v[120:121], off
	s_waitcnt vmcnt(0) lgkmcnt(0)
	v_pk_fma_f32 v[122:123], v[122:123], v[130:131], v[126:127]
	v_pk_fma_f32 v[124:125], v[124:125], v[132:133], v[128:129]
	v_or_b32_e32 v130, v176, v171
	global_store_dwordx4 v[118:119], v[122:125], off
	v_cmp_gt_i32_e32 vcc, s39, v130
	s_nop 0
	v_ashrrev_i32_e32 v122, 31, v130
	v_add_u32_e32 v124, 0xffff8000, v130
	v_cndmask_b32_e32 v123, 0, v122, vcc
	v_cndmask_b32_e32 v122, v124, v130, vcc
	v_cndmask_b32_e32 v125, v160, v161, vcc
	v_cndmask_b32_e32 v124, v162, v163, vcc
	v_lshlrev_b64 v[122:123], 12, v[122:123]
	v_lshl_add_u64 v[124:125], v[124:125], 0, v[122:123]
	v_cndmask_b32_e32 v127, v164, v165, vcc
	v_cndmask_b32_e32 v126, v166, v167, vcc
	v_lshl_add_u64 v[128:129], v[126:127], 0, v[122:123]
	v_lshl_add_u64 v[122:123], v[124:125], 0, v[96:97]
	v_min_i32_e32 v124, 0x8000, v130
	v_ashrrev_i32_e32 v124, 12, v124
	v_mul_hi_i32_i24_e32 v125, 0x6000, v124
	v_mul_i32_i24_e32 v124, 0x6000, v124
	v_lshl_add_u64 v[124:125], s[0:1], 0, v[124:125]
	v_lshl_add_u64 v[126:127], v[124:125], 0, v[96:97]
	v_lshl_add_u64 v[124:125], v[128:129], 0, v[96:97]
	ds_read_b128 v[128:131], v146 offset:4352
	global_load_dwordx4 v[132:135], v[122:123], off
	global_load_dwordx4 v[136:139], v[126:127], off
	s_waitcnt vmcnt(0) lgkmcnt(0)
	v_pk_fma_f32 v[128:129], v[128:129], v[136:137], v[132:133]
	v_pk_fma_f32 v[130:131], v[130:131], v[138:139], v[134:135]
	v_or_b32_e32 v136, v176, v172
	global_store_dwordx4 v[124:125], v[128:131], off
	v_cmp_gt_i32_e32 vcc, s39, v136
	s_nop 0
	v_ashrrev_i32_e32 v128, 31, v136
	v_add_u32_e32 v130, 0xffff8000, v136
	v_cndmask_b32_e32 v129, 0, v128, vcc
	v_cndmask_b32_e32 v128, v130, v136, vcc
	v_cndmask_b32_e32 v131, v160, v161, vcc
	v_cndmask_b32_e32 v130, v162, v163, vcc
	v_lshlrev_b64 v[128:129], 12, v[128:129]
	v_lshl_add_u64 v[130:131], v[130:131], 0, v[128:129]
	v_cndmask_b32_e32 v133, v164, v165, vcc
	v_cndmask_b32_e32 v132, v166, v167, vcc
	v_lshl_add_u64 v[134:135], v[132:133], 0, v[128:129]
	v_lshl_add_u64 v[128:129], v[130:131], 0, v[96:97]
	v_min_i32_e32 v130, 0x8000, v136
	v_ashrrev_i32_e32 v130, 12, v130
	v_mul_hi_i32_i24_e32 v131, 0x6000, v130
	v_mul_i32_i24_e32 v130, 0x6000, v130
	v_lshl_add_u64 v[130:131], s[0:1], 0, v[130:131]
	v_lshl_add_u64 v[132:133], v[130:131], 0, v[96:97]
	v_lshl_add_u64 v[130:131], v[134:135], 0, v[96:97]
	ds_read_b128 v[134:137], v146 offset:5440
	global_load_dwordx4 v[138:141], v[128:129], off
	global_load_dwordx4 v[142:145], v[132:133], off
	s_waitcnt vmcnt(0) lgkmcnt(0)
	v_pk_fma_f32 v[134:135], v[134:135], v[142:143], v[138:139]
	v_pk_fma_f32 v[136:137], v[136:137], v[144:145], v[140:141]
	v_or_b32_e32 v142, v176, v173
	global_store_dwordx4 v[130:131], v[134:137], off
	v_cmp_gt_i32_e32 vcc, s39, v142
	s_nop 0
	v_ashrrev_i32_e32 v134, 31, v142
	v_add_u32_e32 v136, 0xffff8000, v142
	v_cndmask_b32_e32 v135, 0, v134, vcc
	v_cndmask_b32_e32 v134, v136, v142, vcc
	v_cndmask_b32_e32 v137, v160, v161, vcc
	v_cndmask_b32_e32 v136, v162, v163, vcc
	v_lshlrev_b64 v[134:135], 12, v[134:135]
	v_lshl_add_u64 v[136:137], v[136:137], 0, v[134:135]
	v_cndmask_b32_e32 v139, v164, v165, vcc
	v_cndmask_b32_e32 v138, v166, v167, vcc
	v_lshl_add_u64 v[140:141], v[138:139], 0, v[134:135]
	v_lshl_add_u64 v[134:135], v[136:137], 0, v[96:97]
	v_min_i32_e32 v136, 0x8000, v142
	v_ashrrev_i32_e32 v136, 12, v136
	v_mul_hi_i32_i24_e32 v137, 0x6000, v136
	v_mul_i32_i24_e32 v136, 0x6000, v136
	v_lshl_add_u64 v[136:137], s[0:1], 0, v[136:137]
	v_lshl_add_u64 v[138:139], v[136:137], 0, v[96:97]
	v_lshl_add_u64 v[136:137], v[140:141], 0, v[96:97]
	ds_read_b128 v[140:143], v146 offset:6528
	global_load_dwordx4 v[184:187], v[134:135], off
	global_load_dwordx4 v[196:199], v[138:139], off
	v_cmp_gt_i32_e32 vcc, s39, v181
	s_waitcnt vmcnt(0) lgkmcnt(0)
	v_pk_fma_f32 v[140:141], v[140:141], v[196:197], v[184:185]
	v_pk_fma_f32 v[142:143], v[142:143], v[198:199], v[186:187]
	global_store_dwordx4 v[136:137], v[140:143], off
	v_cndmask_b32_e32 v145, v164, v165, vcc
	v_cndmask_b32_e32 v144, v166, v167, vcc
	v_ashrrev_i32_e32 v140, 31, v181
	v_add_u32_e32 v142, 0xffff8000, v181
	v_cndmask_b32_e32 v141, 0, v140, vcc
	v_cndmask_b32_e32 v140, v142, v181, vcc
	v_cndmask_b32_e32 v143, v160, v161, vcc
	v_cndmask_b32_e32 v142, v162, v163, vcc
	v_lshlrev_b64 v[140:141], 12, v[140:141]
	v_lshl_add_u64 v[142:143], v[142:143], 0, v[140:141]
	v_lshl_add_u64 v[184:185], v[144:145], 0, v[140:141]
	v_lshl_add_u64 v[140:141], v[142:143], 0, v[96:97]
	v_min_i32_e32 v142, 0x8000, v181
	v_ashrrev_i32_e32 v142, 12, v142
	v_mul_hi_i32_i24_e32 v143, 0x6000, v142
	v_mul_i32_i24_e32 v142, 0x6000, v142
	v_lshl_add_u64 v[142:143], s[0:1], 0, v[142:143]
	v_lshl_add_u64 v[144:145], v[142:143], 0, v[96:97]
	v_lshl_add_u64 v[142:143], v[184:185], 0, v[96:97]
	ds_read_b128 v[184:187], v146 offset:7616
	global_load_dwordx4 v[196:199], v[140:141], off
	global_load_dwordx4 v[200:203], v[144:145], off
	s_waitcnt vmcnt(0) lgkmcnt(0)
	v_pk_fma_f32 v[184:185], v[184:185], v[200:201], v[196:197]
	v_pk_fma_f32 v[186:187], v[186:187], v[202:203], v[198:199]
	global_store_dwordx4 v[142:143], v[184:187], off
	s_waitcnt lgkmcnt(0)
	ds_write2_b32 v147, v80, v81 offset1:68
	ds_write2_b32 v148, v64, v65 offset0:32 offset1:100
	ds_write2_b32 v147, v82, v83 offset0:136 offset1:204
	ds_write2_b32 v148, v66, v67 offset0:168 offset1:236
	ds_write2_b32 v149, v84, v85 offset0:32 offset1:100
	ds_write2_b32 v150, v68, v69 offset0:64 offset1:132
	ds_write2_b32 v149, v86, v87 offset0:168 offset1:236
	ds_write2_b32 v151, v70, v71 offset0:72 offset1:140
	ds_write2_b32 v152, v88, v89 offset0:64 offset1:132
	ds_write2_b32 v153, v72, v73 offset0:96 offset1:164
	ds_write2_b32 v154, v90, v91 offset0:72 offset1:140
	ds_write2_b32 v155, v74, v75 offset0:104 offset1:172
	ds_write2_b32 v156, v92, v93 offset0:96 offset1:164
	ds_write2_b32 v157, v76, v77 offset0:128 offset1:196
	ds_write2_b32 v158, v94, v95 offset0:104 offset1:172
	ds_write2_b32 v159, v78, v79 offset0:8 offset1:76
	s_waitcnt lgkmcnt(0)
	ds_read_b128 v[64:67], v146
	global_load_dwordx4 v[68:71], v[98:99], off offset:256
	global_load_dwordx4 v[72:75], v[102:103], off offset:256
	s_waitcnt vmcnt(0) lgkmcnt(0)
	v_pk_fma_f32 v[64:65], v[64:65], v[72:73], v[68:69]
	v_pk_fma_f32 v[66:67], v[66:67], v[74:75], v[70:71]
	global_store_dwordx4 v[100:101], v[64:67], off offset:256
	ds_read_b128 v[64:67], v146 offset:1088
	global_load_dwordx4 v[68:71], v[106:107], off offset:256
	global_load_dwordx4 v[72:75], v[108:109], off offset:256
	s_waitcnt vmcnt(0) lgkmcnt(0)
	v_pk_fma_f32 v[64:65], v[64:65], v[72:73], v[68:69]
	v_pk_fma_f32 v[66:67], v[66:67], v[74:75], v[70:71]
	global_store_dwordx4 v[104:105], v[64:67], off offset:256
	ds_read_b128 v[64:67], v146 offset:2176
	global_load_dwordx4 v[68:71], v[110:111], off offset:256
	global_load_dwordx4 v[72:75], v[114:115], off offset:256
	s_waitcnt vmcnt(0) lgkmcnt(0)
	v_pk_fma_f32 v[64:65], v[64:65], v[72:73], v[68:69]
	v_pk_fma_f32 v[66:67], v[66:67], v[74:75], v[70:71]
	global_store_dwordx4 v[112:113], v[64:67], off offset:256
	ds_read_b128 v[64:67], v146 offset:3264
	global_load_dwordx4 v[68:71], v[116:117], off offset:256
	global_load_dwordx4 v[72:75], v[120:121], off offset:256
	s_waitcnt vmcnt(0) lgkmcnt(0)
	v_pk_fma_f32 v[64:65], v[64:65], v[72:73], v[68:69]
	v_pk_fma_f32 v[66:67], v[66:67], v[74:75], v[70:71]
	global_store_dwordx4 v[118:119], v[64:67], off offset:256
	ds_read_b128 v[64:67], v146 offset:4352
	global_load_dwordx4 v[68:71], v[122:123], off offset:256
	global_load_dwordx4 v[72:75], v[126:127], off offset:256
	s_waitcnt vmcnt(0) lgkmcnt(0)
	v_pk_fma_f32 v[64:65], v[64:65], v[72:73], v[68:69]
	v_pk_fma_f32 v[66:67], v[66:67], v[74:75], v[70:71]
	global_store_dwordx4 v[124:125], v[64:67], off offset:256
	ds_read_b128 v[64:67], v146 offset:5440
	global_load_dwordx4 v[68:71], v[128:129], off offset:256
	global_load_dwordx4 v[72:75], v[132:133], off offset:256
	s_waitcnt vmcnt(0) lgkmcnt(0)
	v_pk_fma_f32 v[64:65], v[64:65], v[72:73], v[68:69]
	v_pk_fma_f32 v[66:67], v[66:67], v[74:75], v[70:71]
	global_store_dwordx4 v[130:131], v[64:67], off offset:256
	ds_read_b128 v[64:67], v146 offset:6528
	global_load_dwordx4 v[68:71], v[134:135], off offset:256
	global_load_dwordx4 v[72:75], v[138:139], off offset:256
	s_waitcnt vmcnt(0) lgkmcnt(0)
	v_pk_fma_f32 v[64:65], v[64:65], v[72:73], v[68:69]
	v_pk_fma_f32 v[66:67], v[66:67], v[74:75], v[70:71]
	global_store_dwordx4 v[136:137], v[64:67], off offset:256
	ds_read_b128 v[64:67], v146 offset:7616
	global_load_dwordx4 v[68:71], v[140:141], off offset:256
	global_load_dwordx4 v[72:75], v[144:145], off offset:256
	s_waitcnt vmcnt(0) lgkmcnt(0)
	v_pk_fma_f32 v[64:65], v[64:65], v[72:73], v[68:69]
	v_pk_fma_f32 v[66:67], v[66:67], v[74:75], v[70:71]
	global_store_dwordx4 v[142:143], v[64:67], off offset:256
	v_or_b32_e32 v74, 32, v176
	s_waitcnt lgkmcnt(0)
	ds_write2_b32 v147, v48, v49 offset1:68
	ds_write2_b32 v148, v32, v33 offset0:32 offset1:100
	ds_write2_b32 v147, v50, v51 offset0:136 offset1:204
	ds_write2_b32 v148, v34, v35 offset0:168 offset1:236
	ds_write2_b32 v149, v52, v53 offset0:32 offset1:100
	ds_write2_b32 v150, v36, v37 offset0:64 offset1:132
	ds_write2_b32 v149, v54, v55 offset0:168 offset1:236
	ds_write2_b32 v151, v38, v39 offset0:72 offset1:140
	ds_write2_b32 v152, v56, v57 offset0:64 offset1:132
	ds_write2_b32 v153, v40, v41 offset0:96 offset1:164
	ds_write2_b32 v154, v58, v59 offset0:72 offset1:140
	ds_write2_b32 v155, v42, v43 offset0:104 offset1:172
	ds_write2_b32 v156, v60, v61 offset0:96 offset1:164
	ds_write2_b32 v157, v44, v45 offset0:128 offset1:196
	ds_write2_b32 v158, v62, v63 offset0:104 offset1:172
	ds_write2_b32 v159, v46, v47 offset0:8 offset1:76
	v_or_b32_e32 v40, v74, v175
	v_cmp_gt_i32_e32 vcc, s39, v40
	v_ashrrev_i32_e32 v32, 31, v40
	v_add_u32_e32 v34, 0xffff8000, v40
	v_cndmask_b32_e32 v33, 0, v32, vcc
	v_cndmask_b32_e32 v32, v34, v40, vcc
	v_cndmask_b32_e32 v35, v160, v161, vcc
	v_cndmask_b32_e32 v34, v162, v163, vcc
	v_lshlrev_b64 v[32:33], 12, v[32:33]
	v_lshl_add_u64 v[34:35], v[34:35], 0, v[32:33]
	v_cndmask_b32_e32 v37, v164, v165, vcc
	v_cndmask_b32_e32 v36, v166, v167, vcc
	v_lshl_add_u64 v[38:39], v[36:37], 0, v[32:33]
	v_lshl_add_u64 v[32:33], v[34:35], 0, v[96:97]
	v_min_i32_e32 v34, 0x8000, v40
	v_ashrrev_i32_e32 v34, 12, v34
	v_mul_hi_i32_i24_e32 v35, 0x6000, v34
	v_mul_i32_i24_e32 v34, 0x6000, v34
	s_waitcnt lgkmcnt(0)
	v_lshl_add_u64 v[34:35], s[0:1], 0, v[34:35]
	v_lshl_add_u64 v[36:37], v[34:35], 0, v[96:97]
	v_lshl_add_u64 v[34:35], v[38:39], 0, v[96:97]
	ds_read_b128 v[38:41], v146
	global_load_dwordx4 v[42:45], v[32:33], off
	global_load_dwordx4 v[46:49], v[36:37], off
	v_or_b32_e32 v75, v74, v173
	s_waitcnt vmcnt(0) lgkmcnt(0)
	v_pk_fma_f32 v[38:39], v[38:39], v[46:47], v[42:43]
	v_pk_fma_f32 v[40:41], v[40:41], v[48:49], v[44:45]
	v_or_b32_e32 v46, v74, v168
	global_store_dwordx4 v[34:35], v[38:41], off
	v_cmp_gt_i32_e32 vcc, s39, v46
	s_nop 0
	v_ashrrev_i32_e32 v38, 31, v46
	v_add_u32_e32 v40, 0xffff8000, v46
	v_cndmask_b32_e32 v39, 0, v38, vcc
	v_cndmask_b32_e32 v38, v40, v46, vcc
	v_cndmask_b32_e32 v41, v160, v161, vcc
	v_cndmask_b32_e32 v40, v162, v163, vcc
	v_lshlrev_b64 v[38:39], 12, v[38:39]
	v_lshl_add_u64 v[40:41], v[40:41], 0, v[38:39]
	v_cndmask_b32_e32 v43, v164, v165, vcc
	v_cndmask_b32_e32 v42, v166, v167, vcc
	v_lshl_add_u64 v[44:45], v[42:43], 0, v[38:39]
	v_lshl_add_u64 v[38:39], v[40:41], 0, v[96:97]
	v_min_i32_e32 v40, 0x8000, v46
	v_ashrrev_i32_e32 v40, 12, v40
	v_mul_hi_i32_i24_e32 v41, 0x6000, v40
	v_mul_i32_i24_e32 v40, 0x6000, v40
	v_lshl_add_u64 v[40:41], s[0:1], 0, v[40:41]
	v_lshl_add_u64 v[42:43], v[40:41], 0, v[96:97]
	v_lshl_add_u64 v[40:41], v[44:45], 0, v[96:97]
	ds_read_b128 v[44:47], v146 offset:1088
	global_load_dwordx4 v[48:51], v[38:39], off
	global_load_dwordx4 v[52:55], v[42:43], off
	s_waitcnt vmcnt(0) lgkmcnt(0)
	v_pk_fma_f32 v[44:45], v[44:45], v[52:53], v[48:49]
	v_pk_fma_f32 v[46:47], v[46:47], v[54:55], v[50:51]
	v_or_b32_e32 v52, v74, v169
	global_store_dwordx4 v[40:41], v[44:47], off
	v_cmp_gt_i32_e32 vcc, s39, v52
	s_nop 0
	v_ashrrev_i32_e32 v44, 31, v52
	v_add_u32_e32 v46, 0xffff8000, v52
	v_cndmask_b32_e32 v45, 0, v44, vcc
	v_cndmask_b32_e32 v44, v46, v52, vcc
	v_cndmask_b32_e32 v47, v160, v161, vcc
	v_cndmask_b32_e32 v46, v162, v163, vcc
	v_lshlrev_b64 v[44:45], 12, v[44:45]
	v_lshl_add_u64 v[46:47], v[46:47], 0, v[44:45]
	v_cndmask_b32_e32 v49, v164, v165, vcc
	v_cndmask_b32_e32 v48, v166, v167, vcc
	v_lshl_add_u64 v[50:51], v[48:49], 0, v[44:45]
	v_lshl_add_u64 v[44:45], v[46:47], 0, v[96:97]
	v_min_i32_e32 v46, 0x8000, v52
	v_ashrrev_i32_e32 v46, 12, v46
	v_mul_hi_i32_i24_e32 v47, 0x6000, v46
	v_mul_i32_i24_e32 v46, 0x6000, v46
	v_lshl_add_u64 v[46:47], s[0:1], 0, v[46:47]
	v_lshl_add_u64 v[48:49], v[46:47], 0, v[96:97]
	v_lshl_add_u64 v[46:47], v[50:51], 0, v[96:97]
	ds_read_b128 v[50:53], v146 offset:2176
	global_load_dwordx4 v[54:57], v[44:45], off
	global_load_dwordx4 v[58:61], v[48:49], off
	s_waitcnt vmcnt(0) lgkmcnt(0)
	v_pk_fma_f32 v[50:51], v[50:51], v[58:59], v[54:55]
	v_pk_fma_f32 v[52:53], v[52:53], v[60:61], v[56:57]
	v_or_b32_e32 v58, v74, v170
	global_store_dwordx4 v[46:47], v[50:53], off
	v_cmp_gt_i32_e32 vcc, s39, v58
	s_nop 0
	v_ashrrev_i32_e32 v50, 31, v58
	v_add_u32_e32 v52, 0xffff8000, v58
	v_cndmask_b32_e32 v51, 0, v50, vcc
	v_cndmask_b32_e32 v50, v52, v58, vcc
	v_cndmask_b32_e32 v53, v160, v161, vcc
	v_cndmask_b32_e32 v52, v162, v163, vcc
	v_lshlrev_b64 v[50:51], 12, v[50:51]
	v_lshl_add_u64 v[52:53], v[52:53], 0, v[50:51]
	v_cndmask_b32_e32 v55, v164, v165, vcc
	v_cndmask_b32_e32 v54, v166, v167, vcc
	v_lshl_add_u64 v[56:57], v[54:55], 0, v[50:51]
	v_lshl_add_u64 v[50:51], v[52:53], 0, v[96:97]
	v_min_i32_e32 v52, 0x8000, v58
	v_ashrrev_i32_e32 v52, 12, v52
	v_mul_hi_i32_i24_e32 v53, 0x6000, v52
	v_mul_i32_i24_e32 v52, 0x6000, v52
	v_lshl_add_u64 v[52:53], s[0:1], 0, v[52:53]
	v_lshl_add_u64 v[54:55], v[52:53], 0, v[96:97]
	v_lshl_add_u64 v[52:53], v[56:57], 0, v[96:97]
	ds_read_b128 v[56:59], v146 offset:3264
	global_load_dwordx4 v[60:63], v[50:51], off
	global_load_dwordx4 v[64:67], v[54:55], off
	s_waitcnt vmcnt(0) lgkmcnt(0)
	v_pk_fma_f32 v[56:57], v[56:57], v[64:65], v[60:61]
	v_pk_fma_f32 v[58:59], v[58:59], v[66:67], v[62:63]
	v_or_b32_e32 v64, v74, v171
	global_store_dwordx4 v[52:53], v[56:59], off
	v_cmp_gt_i32_e32 vcc, s39, v64
	s_nop 0
	v_ashrrev_i32_e32 v56, 31, v64
	v_add_u32_e32 v58, 0xffff8000, v64
	v_cndmask_b32_e32 v57, 0, v56, vcc
	v_cndmask_b32_e32 v56, v58, v64, vcc
	v_cndmask_b32_e32 v59, v160, v161, vcc
	v_cndmask_b32_e32 v58, v162, v163, vcc
	v_lshlrev_b64 v[56:57], 12, v[56:57]
	v_lshl_add_u64 v[58:59], v[58:59], 0, v[56:57]
	v_cndmask_b32_e32 v61, v164, v165, vcc
	v_cndmask_b32_e32 v60, v166, v167, vcc
	v_lshl_add_u64 v[62:63], v[60:61], 0, v[56:57]
	v_lshl_add_u64 v[56:57], v[58:59], 0, v[96:97]
	v_min_i32_e32 v58, 0x8000, v64
	v_ashrrev_i32_e32 v58, 12, v58
	v_mul_hi_i32_i24_e32 v59, 0x6000, v58
	v_mul_i32_i24_e32 v58, 0x6000, v58
	v_lshl_add_u64 v[58:59], s[0:1], 0, v[58:59]
	v_lshl_add_u64 v[60:61], v[58:59], 0, v[96:97]
	v_lshl_add_u64 v[58:59], v[62:63], 0, v[96:97]
	ds_read_b128 v[62:65], v146 offset:4352
	global_load_dwordx4 v[66:69], v[56:57], off
	global_load_dwordx4 v[70:73], v[60:61], off
	s_waitcnt vmcnt(0) lgkmcnt(0)
	v_pk_fma_f32 v[62:63], v[62:63], v[70:71], v[66:67]
	v_pk_fma_f32 v[64:65], v[64:65], v[72:73], v[68:69]
	v_or_b32_e32 v70, v74, v172
	global_store_dwordx4 v[58:59], v[62:65], off
	v_cmp_gt_i32_e32 vcc, s39, v70
	s_nop 0
	v_ashrrev_i32_e32 v62, 31, v70
	v_add_u32_e32 v64, 0xffff8000, v70
	v_cndmask_b32_e32 v63, 0, v62, vcc
	v_cndmask_b32_e32 v62, v64, v70, vcc
	v_cndmask_b32_e32 v65, v160, v161, vcc
	v_cndmask_b32_e32 v64, v162, v163, vcc
	v_lshlrev_b64 v[62:63], 12, v[62:63]
	v_lshl_add_u64 v[64:65], v[64:65], 0, v[62:63]
	v_cndmask_b32_e32 v67, v164, v165, vcc
	v_cndmask_b32_e32 v66, v166, v167, vcc
	v_lshl_add_u64 v[68:69], v[66:67], 0, v[62:63]
	v_lshl_add_u64 v[62:63], v[64:65], 0, v[96:97]
	v_min_i32_e32 v64, 0x8000, v70
	v_ashrrev_i32_e32 v64, 12, v64
	v_mul_hi_i32_i24_e32 v65, 0x6000, v64
	v_mul_i32_i24_e32 v64, 0x6000, v64
	v_lshl_add_u64 v[64:65], s[0:1], 0, v[64:65]
	v_lshl_add_u64 v[66:67], v[64:65], 0, v[96:97]
	v_lshl_add_u64 v[64:65], v[68:69], 0, v[96:97]
	ds_read_b128 v[68:71], v146 offset:5440
	global_load_dwordx4 v[76:79], v[62:63], off
	global_load_dwordx4 v[80:83], v[66:67], off
	v_cmp_gt_i32_e32 vcc, s39, v75
	s_waitcnt vmcnt(0) lgkmcnt(0)
	v_pk_fma_f32 v[68:69], v[68:69], v[80:81], v[76:77]
	v_pk_fma_f32 v[70:71], v[70:71], v[82:83], v[78:79]
	global_store_dwordx4 v[64:65], v[68:71], off
	v_cndmask_b32_e32 v73, v164, v165, vcc
	v_cndmask_b32_e32 v72, v166, v167, vcc
	v_ashrrev_i32_e32 v68, 31, v75
	v_add_u32_e32 v70, 0xffff8000, v75
	v_cndmask_b32_e32 v69, 0, v68, vcc
	v_cndmask_b32_e32 v68, v70, v75, vcc
	v_cndmask_b32_e32 v71, v160, v161, vcc
	v_cndmask_b32_e32 v70, v162, v163, vcc
	v_lshlrev_b64 v[68:69], 12, v[68:69]
	v_lshl_add_u64 v[70:71], v[70:71], 0, v[68:69]
	v_lshl_add_u64 v[76:77], v[72:73], 0, v[68:69]
	v_lshl_add_u64 v[68:69], v[70:71], 0, v[96:97]
	v_min_i32_e32 v70, 0x8000, v75
	v_ashrrev_i32_e32 v70, 12, v70
	v_mul_hi_i32_i24_e32 v71, 0x6000, v70
	v_mul_i32_i24_e32 v70, 0x6000, v70
	v_lshl_add_u64 v[70:71], s[0:1], 0, v[70:71]
	v_lshl_add_u64 v[72:73], v[70:71], 0, v[96:97]
	v_lshl_add_u64 v[70:71], v[76:77], 0, v[96:97]
	ds_read_b128 v[76:79], v146 offset:6528
	global_load_dwordx4 v[80:83], v[68:69], off
	global_load_dwordx4 v[84:87], v[72:73], off
	s_waitcnt vmcnt(0) lgkmcnt(0)
	v_pk_fma_f32 v[76:77], v[76:77], v[84:85], v[80:81]
	v_pk_fma_f32 v[78:79], v[78:79], v[86:87], v[82:83]
	v_or_b32_e32 v82, v74, v174
	global_store_dwordx4 v[70:71], v[76:79], off
	v_cmp_gt_i32_e32 vcc, s39, v82
	v_ashrrev_i32_e32 v74, 31, v82
	v_add_u32_e32 v76, 0xffff8000, v82
	v_cndmask_b32_e32 v75, 0, v74, vcc
	v_cndmask_b32_e32 v74, v76, v82, vcc
	v_cndmask_b32_e32 v77, v160, v161, vcc
	v_cndmask_b32_e32 v76, v162, v163, vcc
	v_lshlrev_b64 v[74:75], 12, v[74:75]
	v_lshl_add_u64 v[76:77], v[76:77], 0, v[74:75]
	v_cndmask_b32_e32 v79, v164, v165, vcc
	v_cndmask_b32_e32 v78, v166, v167, vcc
	v_lshl_add_u64 v[80:81], v[78:79], 0, v[74:75]
	v_lshl_add_u64 v[74:75], v[76:77], 0, v[96:97]
	v_min_i32_e32 v76, 0x8000, v82
	v_ashrrev_i32_e32 v76, 12, v76
	v_mul_hi_i32_i24_e32 v77, 0x6000, v76
	v_mul_i32_i24_e32 v76, 0x6000, v76
	v_lshl_add_u64 v[76:77], s[0:1], 0, v[76:77]
	v_lshl_add_u64 v[78:79], v[76:77], 0, v[96:97]
	v_lshl_add_u64 v[76:77], v[80:81], 0, v[96:97]
	ds_read_b128 v[80:83], v146 offset:7616
	global_load_dwordx4 v[84:87], v[74:75], off
	global_load_dwordx4 v[88:91], v[78:79], off
	s_waitcnt vmcnt(0) lgkmcnt(0)
	v_pk_fma_f32 v[80:81], v[80:81], v[88:89], v[84:85]
	v_pk_fma_f32 v[82:83], v[82:83], v[90:91], v[86:87]
	global_store_dwordx4 v[76:77], v[80:83], off
	s_waitcnt lgkmcnt(0)
	ds_write2_b32 v147, v16, v17 offset1:68
	ds_write2_b32 v148, v0, v1 offset0:32 offset1:100
	ds_write2_b32 v147, v18, v19 offset0:136 offset1:204
	ds_write2_b32 v148, v2, v3 offset0:168 offset1:236
	ds_write2_b32 v149, v20, v21 offset0:32 offset1:100
	ds_write2_b32 v150, v4, v5 offset0:64 offset1:132
	ds_write2_b32 v149, v22, v23 offset0:168 offset1:236
	ds_write2_b32 v151, v6, v7 offset0:72 offset1:140
	ds_write2_b32 v152, v24, v25 offset0:64 offset1:132
	ds_write2_b32 v153, v8, v9 offset0:96 offset1:164
	ds_write2_b32 v154, v26, v27 offset0:72 offset1:140
	ds_write2_b32 v155, v10, v11 offset0:104 offset1:172
	ds_write2_b32 v156, v28, v29 offset0:96 offset1:164
	ds_write2_b32 v157, v12, v13 offset0:128 offset1:196
	ds_write2_b32 v158, v30, v31 offset0:104 offset1:172
	ds_write2_b32 v159, v14, v15 offset0:8 offset1:76
	s_waitcnt lgkmcnt(0)
	ds_read_b128 v[0:3], v146
	global_load_dwordx4 v[4:7], v[32:33], off offset:256
	global_load_dwordx4 v[8:11], v[36:37], off offset:256
	s_waitcnt vmcnt(0) lgkmcnt(0)
	v_pk_fma_f32 v[0:1], v[0:1], v[8:9], v[4:5]
	v_pk_fma_f32 v[2:3], v[2:3], v[10:11], v[6:7]
	global_store_dwordx4 v[34:35], v[0:3], off offset:256
	ds_read_b128 v[0:3], v146 offset:1088
	global_load_dwordx4 v[4:7], v[38:39], off offset:256
	global_load_dwordx4 v[8:11], v[42:43], off offset:256
	s_waitcnt vmcnt(0) lgkmcnt(0)
	v_pk_fma_f32 v[0:1], v[0:1], v[8:9], v[4:5]
	v_pk_fma_f32 v[2:3], v[2:3], v[10:11], v[6:7]
	global_store_dwordx4 v[40:41], v[0:3], off offset:256
	ds_read_b128 v[0:3], v146 offset:2176
	global_load_dwordx4 v[4:7], v[44:45], off offset:256
	global_load_dwordx4 v[8:11], v[48:49], off offset:256
	s_waitcnt vmcnt(0) lgkmcnt(0)
	v_pk_fma_f32 v[0:1], v[0:1], v[8:9], v[4:5]
	v_pk_fma_f32 v[2:3], v[2:3], v[10:11], v[6:7]
	global_store_dwordx4 v[46:47], v[0:3], off offset:256
	ds_read_b128 v[0:3], v146 offset:3264
	global_load_dwordx4 v[4:7], v[50:51], off offset:256
	global_load_dwordx4 v[8:11], v[54:55], off offset:256
	s_waitcnt vmcnt(0) lgkmcnt(0)
	v_pk_fma_f32 v[0:1], v[0:1], v[8:9], v[4:5]
	v_pk_fma_f32 v[2:3], v[2:3], v[10:11], v[6:7]
	global_store_dwordx4 v[52:53], v[0:3], off offset:256
	ds_read_b128 v[0:3], v146 offset:4352
	global_load_dwordx4 v[4:7], v[56:57], off offset:256
	global_load_dwordx4 v[8:11], v[60:61], off offset:256
	s_waitcnt vmcnt(0) lgkmcnt(0)
	v_pk_fma_f32 v[0:1], v[0:1], v[8:9], v[4:5]
	v_pk_fma_f32 v[2:3], v[2:3], v[10:11], v[6:7]
	global_store_dwordx4 v[58:59], v[0:3], off offset:256
	ds_read_b128 v[0:3], v146 offset:5440
	global_load_dwordx4 v[4:7], v[62:63], off offset:256
	global_load_dwordx4 v[8:11], v[66:67], off offset:256
	s_waitcnt vmcnt(0) lgkmcnt(0)
	v_pk_fma_f32 v[0:1], v[0:1], v[8:9], v[4:5]
	v_pk_fma_f32 v[2:3], v[2:3], v[10:11], v[6:7]
	global_store_dwordx4 v[64:65], v[0:3], off offset:256
	ds_read_b128 v[0:3], v146 offset:6528
	global_load_dwordx4 v[4:7], v[68:69], off offset:256
	global_load_dwordx4 v[8:11], v[72:73], off offset:256
	s_waitcnt vmcnt(0) lgkmcnt(0)
	v_pk_fma_f32 v[0:1], v[0:1], v[8:9], v[4:5]
	v_pk_fma_f32 v[2:3], v[2:3], v[10:11], v[6:7]
	global_store_dwordx4 v[70:71], v[0:3], off offset:256
	ds_read_b128 v[0:3], v146 offset:7616
	global_load_dwordx4 v[4:7], v[74:75], off offset:256
	global_load_dwordx4 v[8:11], v[78:79], off offset:256
	s_waitcnt vmcnt(0) lgkmcnt(0)
	v_pk_fma_f32 v[0:1], v[0:1], v[8:9], v[4:5]
	v_pk_fma_f32 v[2:3], v[2:3], v[10:11], v[6:7]
	global_store_dwordx4 v[76:77], v[0:3], off offset:256
	s_waitcnt lgkmcnt(0)
	s_barrier
	s_cbranch_scc1 .LBB0_923

.LBB0_1086:
	s_ashr_i32 s6, s2, 31
	s_lshr_b32 s6, s6, 26
	s_add_i32 s6, s2, s6
	s_ashr_i32 s7, s6, 6
	s_lshl_b32 s7, s7, 3
	s_sub_i32 s8, s25, s7
	s_min_i32 s8, s8, 8
	s_abs_i32 s9, s8
	v_cvt_f32_u32_e32 v0, s9
	s_sub_i32 s12, 0, s9
	s_andn2_b32 s6, s6, 63
	s_sub_i32 s10, s2, s6
	v_rcp_iflag_f32_e32 v0, v0
	s_abs_i32 s6, s10
	s_xor_b32 s11, s10, s8
	s_ashr_i32 s11, s11, 31
	v_mul_f32_e32 v0, 0x4f7ffffe, v0
	v_cvt_u32_f32_e32 v0, v0
	v_mov_b32_e32 v181, v179
	v_readfirstlane_b32 s13, v0
	s_mul_i32 s12, s12, s13
	s_mul_hi_u32 s12, s13, s12
	s_add_i32 s13, s13, s12
	s_mul_hi_u32 s12, s6, s13
	s_mul_i32 s13, s12, s9
	s_sub_i32 s6, s6, s13
	s_add_i32 s14, s12, 1
	s_sub_i32 s13, s6, s9
	s_cmp_ge_u32 s6, s9
	s_cselect_b32 s12, s14, s12
	s_cselect_b32 s6, s13, s6
	s_add_i32 s13, s12, 1
	s_cmp_ge_u32 s6, s9
	s_cselect_b32 s6, s13, s12
	s_xor_b32 s6, s6, s11
	s_sub_i32 s6, s6, s11
	s_mul_i32 s8, s8, s6
	s_add_i32 s7, s7, s5
	s_sub_i32 s8, s10, s8
	v_ashrrev_i32_e32 v237, 6, v181
	s_add_i32 s7, s7, s8
	v_lshlrev_b32_e32 v0, 1, v237
	v_bfe_u32 v183, v181, 5, 1
	v_lshl_add_u32 v2, s7, 3, v0
	v_mov_b64_e32 v[0:1], s[66:67]
	v_and_b32_e32 v238, 31, v181
	v_mad_i64_i32 v[0:1], s[8:9], v2, s24, v[0:1]
	v_lshlrev_b32_e32 v176, 9, v183
	v_lshl_add_u64 v[0:1], v[0:1], 0, v[176:177]
	v_lshlrev_b32_e32 v176, 4, v238
	v_ashrrev_i32_e32 v38, 2, v181
	s_mul_i32 s8, s6, 0xb0000
	v_lshl_add_u64 v[184:185], v[0:1], 0, v[176:177]
	s_mul_hi_i32 s9, s6, 0xb0000
	s_add_u32 s8, s3, s8
	v_lshlrev_b32_e32 v0, 5, v38
	s_addc_u32 s9, s4, s9
	v_ashrrev_i32_e32 v1, 31, v0
	v_lshlrev_b32_e32 v2, 4, v181
	v_lshl_add_u64 v[0:1], v[0:1], 1, s[8:9]
	v_and_b32_e32 v176, 48, v2
	v_lshl_add_u64 v[186:187], v[0:1], 0, v[176:177]
	s_movk_i32 s8, 0x2000
	v_add_co_u32_e32 v34, vcc, s8, v186
	v_mul_u32_u24_e32 v36, 40, v238
	s_nop 0
	v_addc_co_u32_e32 v35, vcc, 0, v187, vcc
	v_lshlrev_b32_e32 v37, 4, v183
	v_lshl_add_u32 v240, v36, 1, v37
	v_add_co_u32_e32 v36, vcc, s24, v184
	s_movk_i32 s9, 0x50
	s_nop 0
	v_addc_co_u32_e32 v37, vcc, 0, v185, vcc
	v_and_b32_e32 v239, 63, v181
	v_mov_b32_e32 v176, 0x800
	v_lshl_add_u64 v[188:189], v[186:187], 0, v[176:177]
	v_bfe_u32 v247, v181, 4, 1
	v_lshlrev_b32_e32 v176, 9, v183
	v_lshl_add_u32 v176, v247, 8, v176
	v_lshl_add_u64 v[184:185], v[184:185], 0, v[176:177]
	v_mov_b32_e32 v176, s24
	v_lshl_add_u64 v[186:187], v[184:185], 0, v[176:177]
	v_lshrrev_b32_e32 v241, 2, v181
	v_bfe_u32 v247, v181, 4, 2
	v_lshlrev_b32_e32 v247, 1, v247
	v_mov_b32_e32 v176, 0x78
	v_lshrrev_b32_e32 v247, v247, v176
	v_and_b32_e32 v247, 3, v247
	v_and_b32_e32 v246, 3, v181
	v_xor_b32_e32 v247, v247, v246
	v_lshlrev_b32_e32 v247, 4, v247
	v_lshl_add_u32 v241, v241, 6, v247
	v_bfe_u32 v247, v181, 2, 2
	v_lshlrev_b32_e32 v247, 1, v247
	v_lshrrev_b32_e32 v247, v247, v176
	v_and_b32_e32 v247, 3, v247
	v_bfe_u32 v246, v181, 4, 2
	v_xor_b32_e32 v247, v247, v246
	v_lshlrev_b32_e32 v247, 4, v247
	v_and_b32_e32 v246, 15, v181
	v_lshl_add_u32 v246, v246, 6, v247
	s_mov_b32 s96, 0
	v_lshl_add_u64 v[166:167], v[188:189], 0, s[96:97]
	global_load_dwordx4 v[160:163], v[166:167], off offset:-2048
	global_load_dwordx4 v[164:167], v[166:167], off offset:2048
	v_lshl_add_u64 v[248:249], v[184:185], 0, s[96:97]
	v_lshl_add_u64 v[250:251], v[186:187], 0, s[96:97]
	global_load_dwordx4 v[128:131], v[248:249], off
	global_load_dwordx4 v[132:135], v[248:249], off offset:256
	global_load_dwordx4 v[136:139], v[250:251], off
	global_load_dwordx4 v[140:143], v[250:251], off offset:256
	s_movk_i32 s96, 0x2000
	v_lshl_add_u64 v[174:175], v[188:189], 0, s[96:97]
	global_load_dwordx4 v[168:171], v[174:175], off offset:-2048
	global_load_dwordx4 v[172:175], v[174:175], off offset:2048
	s_movk_i32 s96, 0x800
	v_lshl_add_u64 v[248:249], v[184:185], 0, s[96:97]
	v_lshl_add_u64 v[250:251], v[186:187], 0, s[96:97]
	global_load_dwordx4 v[144:147], v[248:249], off
	global_load_dwordx4 v[148:151], v[248:249], off offset:256
	global_load_dwordx4 v[152:155], v[250:251], off
	global_load_dwordx4 v[156:159], v[250:251], off offset:256
	v_mov_b32_e32 v0, 0
	v_mov_b32_e32 v1, 0
	v_mov_b32_e32 v2, 0
	v_mov_b32_e32 v3, 0
	v_mov_b32_e32 v4, 0
	v_mov_b32_e32 v5, 0
	v_mov_b32_e32 v6, 0
	v_mov_b32_e32 v7, 0
	v_mov_b32_e32 v8, 0
	v_mov_b32_e32 v9, 0
	v_mov_b32_e32 v10, 0
	v_mov_b32_e32 v11, 0
	v_mov_b32_e32 v12, 0
	v_mov_b32_e32 v13, 0
	v_mov_b32_e32 v14, 0
	v_mov_b32_e32 v15, 0
	v_mov_b32_e32 v16, 0
	v_mov_b32_e32 v17, 0
	v_mov_b32_e32 v18, 0
	v_mov_b32_e32 v19, 0
	v_mov_b32_e32 v20, 0
	v_mov_b32_e32 v21, 0
	v_mov_b32_e32 v22, 0
	v_mov_b32_e32 v23, 0
	v_mov_b32_e32 v24, 0
	v_mov_b32_e32 v25, 0
	v_mov_b32_e32 v26, 0
	v_mov_b32_e32 v27, 0
	v_mov_b32_e32 v28, 0
	v_mov_b32_e32 v29, 0
	v_mov_b32_e32 v30, 0
	v_mov_b32_e32 v31, 0
	v_mov_b32_e32 v32, 0
	v_mov_b32_e32 v33, 0
	v_mov_b32_e32 v34, 0
	v_mov_b32_e32 v35, 0
	v_mov_b32_e32 v36, 0
	v_mov_b32_e32 v37, 0
	v_mov_b32_e32 v38, 0
	v_mov_b32_e32 v39, 0
	v_mov_b32_e32 v40, 0
	v_mov_b32_e32 v41, 0
	v_mov_b32_e32 v42, 0
	v_mov_b32_e32 v43, 0
	v_mov_b32_e32 v44, 0
	v_mov_b32_e32 v45, 0
	v_mov_b32_e32 v46, 0
	v_mov_b32_e32 v47, 0
	v_mov_b32_e32 v48, 0
	v_mov_b32_e32 v49, 0
	v_mov_b32_e32 v50, 0
	v_mov_b32_e32 v51, 0
	v_mov_b32_e32 v52, 0
	v_mov_b32_e32 v53, 0
	v_mov_b32_e32 v54, 0
	v_mov_b32_e32 v55, 0
	v_mov_b32_e32 v56, 0
	v_mov_b32_e32 v57, 0
	v_mov_b32_e32 v58, 0
	v_mov_b32_e32 v59, 0
	v_mov_b32_e32 v60, 0
	v_mov_b32_e32 v61, 0
	v_mov_b32_e32 v62, 0
	v_mov_b32_e32 v63, 0
	v_mov_b32_e32 v64, 0
	v_mov_b32_e32 v65, 0
	v_mov_b32_e32 v66, 0
	v_mov_b32_e32 v67, 0
	v_mov_b32_e32 v68, 0
	v_mov_b32_e32 v69, 0
	v_mov_b32_e32 v70, 0
	v_mov_b32_e32 v71, 0
	v_mov_b32_e32 v72, 0
	v_mov_b32_e32 v73, 0
	v_mov_b32_e32 v74, 0
	v_mov_b32_e32 v75, 0
	v_mov_b32_e32 v76, 0
	v_mov_b32_e32 v77, 0
	v_mov_b32_e32 v78, 0
	v_mov_b32_e32 v79, 0
	v_mov_b32_e32 v80, 0
	v_mov_b32_e32 v81, 0
	v_mov_b32_e32 v82, 0
	v_mov_b32_e32 v83, 0
	v_mov_b32_e32 v84, 0
	v_mov_b32_e32 v85, 0
	v_mov_b32_e32 v86, 0
	v_mov_b32_e32 v87, 0
	v_mov_b32_e32 v88, 0
	v_mov_b32_e32 v89, 0
	v_mov_b32_e32 v90, 0
	v_mov_b32_e32 v91, 0
	v_mov_b32_e32 v92, 0
	v_mov_b32_e32 v93, 0
	v_mov_b32_e32 v94, 0
	v_mov_b32_e32 v95, 0
	v_mov_b32_e32 v96, 0
	v_mov_b32_e32 v97, 0
	v_mov_b32_e32 v98, 0
	v_mov_b32_e32 v99, 0
	v_mov_b32_e32 v100, 0
	v_mov_b32_e32 v101, 0
	v_mov_b32_e32 v102, 0
	v_mov_b32_e32 v103, 0
	v_mov_b32_e32 v104, 0
	v_mov_b32_e32 v105, 0
	v_mov_b32_e32 v106, 0
	v_mov_b32_e32 v107, 0
	v_mov_b32_e32 v108, 0
	v_mov_b32_e32 v109, 0
	v_mov_b32_e32 v110, 0
	v_mov_b32_e32 v111, 0
	v_mov_b32_e32 v112, 0
	v_mov_b32_e32 v113, 0
	v_mov_b32_e32 v114, 0
	v_mov_b32_e32 v115, 0
	v_mov_b32_e32 v116, 0
	v_mov_b32_e32 v117, 0
	v_mov_b32_e32 v118, 0
	v_mov_b32_e32 v119, 0
	v_mov_b32_e32 v120, 0
	v_mov_b32_e32 v121, 0
	v_mov_b32_e32 v122, 0
	v_mov_b32_e32 v123, 0
	v_mov_b32_e32 v124, 0
	v_mov_b32_e32 v125, 0
	v_mov_b32_e32 v126, 0
	v_mov_b32_e32 v127, 0
	s_mov_b32 s8, 0
	s_waitcnt vmcnt(10)
	ds_write_b128 v241, v[160:163]
	ds_write_b128 v241, v[164:167] offset:4096
	s_waitcnt lgkmcnt(0)
	s_barrier
.Lg16_down_k:
	s_add_i32 s9, s8, 2
	s_min_u32 s10, s9, 86
	s_lshl_b32 s96, s10, 13
	v_lshl_add_u64 v[166:167], v[188:189], 0, s[96:97]
	global_load_dwordx4 v[160:163], v[166:167], off offset:-2048
	global_load_dwordx4 v[164:167], v[166:167], off offset:2048
	ds_read_b128 v[196:199], v246 offset:0
	ds_read_b128 v[200:203], v246 offset:1024
	ds_read_b128 v[204:207], v246 offset:2048
	ds_read_b128 v[242:245], v246 offset:3072
	s_lshl_b32 s96, s10, 11
	v_lshl_add_u64 v[248:249], v[184:185], 0, s[96:97]
	v_lshl_add_u64 v[250:251], v[186:187], 0, s[96:97]
	s_waitcnt vmcnt(8) lgkmcnt(3)
	v_mfma_f32_16x16x32_bf16 v[112:115], v[128:131], v[196:199], v[112:115]
	v_mfma_f32_16x16x32_bf16 v[120:123], v[132:135], v[196:199], v[120:123]
	v_mfma_f32_16x16x32_bf16 v[48:51], v[136:139], v[196:199], v[48:51]
	v_mfma_f32_16x16x32_bf16 v[56:59], v[140:143], v[196:199], v[56:59]
	ds_read_b128 v[196:199], v246 offset:4096
	s_waitcnt lgkmcnt(3)
	v_mfma_f32_16x16x32_bf16 v[116:119], v[128:131], v[200:203], v[116:119]
	v_mfma_f32_16x16x32_bf16 v[124:127], v[132:135], v[200:203], v[124:127]
	v_mfma_f32_16x16x32_bf16 v[52:55], v[136:139], v[200:203], v[52:55]
	v_mfma_f32_16x16x32_bf16 v[60:63], v[140:143], v[200:203], v[60:63]
	ds_read_b128 v[200:203], v246 offset:5120
	s_waitcnt lgkmcnt(3)
	v_mfma_f32_16x16x32_bf16 v[96:99], v[128:131], v[204:207], v[96:99]
	v_mfma_f32_16x16x32_bf16 v[104:107], v[132:135], v[204:207], v[104:107]
	v_mfma_f32_16x16x32_bf16 v[32:35], v[136:139], v[204:207], v[32:35]
	v_mfma_f32_16x16x32_bf16 v[40:43], v[140:143], v[204:207], v[40:43]
	ds_read_b128 v[204:207], v246 offset:6144
	s_waitcnt lgkmcnt(3)
	v_mfma_f32_16x16x32_bf16 v[100:103], v[128:131], v[242:245], v[100:103]
	v_mfma_f32_16x16x32_bf16 v[108:111], v[132:135], v[242:245], v[108:111]
	v_mfma_f32_16x16x32_bf16 v[36:39], v[136:139], v[242:245], v[36:39]
	v_mfma_f32_16x16x32_bf16 v[44:47], v[140:143], v[242:245], v[44:47]
	ds_read_b128 v[242:245], v246 offset:7168
	s_waitcnt vmcnt(6)
	ds_write_b128 v241, v[168:171] offset:8192
	ds_write_b128 v241, v[172:175] offset:12288
	s_waitcnt lgkmcnt(5)
	v_mfma_f32_16x16x32_bf16 v[80:83], v[128:131], v[196:199], v[80:83]
	v_mfma_f32_16x16x32_bf16 v[88:91], v[132:135], v[196:199], v[88:91]
	v_mfma_f32_16x16x32_bf16 v[16:19], v[136:139], v[196:199], v[16:19]
	v_mfma_f32_16x16x32_bf16 v[24:27], v[140:143], v[196:199], v[24:27]
	s_waitcnt lgkmcnt(4)
	v_mfma_f32_16x16x32_bf16 v[84:87], v[128:131], v[200:203], v[84:87]
	v_mfma_f32_16x16x32_bf16 v[92:95], v[132:135], v[200:203], v[92:95]
	v_mfma_f32_16x16x32_bf16 v[20:23], v[136:139], v[200:203], v[20:23]
	v_mfma_f32_16x16x32_bf16 v[28:31], v[140:143], v[200:203], v[28:31]
	s_waitcnt lgkmcnt(3)
	v_mfma_f32_16x16x32_bf16 v[64:67], v[128:131], v[204:207], v[64:67]
	v_mfma_f32_16x16x32_bf16 v[72:75], v[132:135], v[204:207], v[72:75]
	v_mfma_f32_16x16x32_bf16 v[0:3], v[136:139], v[204:207], v[0:3]
	v_mfma_f32_16x16x32_bf16 v[8:11], v[140:143], v[204:207], v[8:11]
	s_waitcnt lgkmcnt(2)
	v_mfma_f32_16x16x32_bf16 v[68:71], v[128:131], v[242:245], v[68:71]
	v_mfma_f32_16x16x32_bf16 v[76:79], v[132:135], v[242:245], v[76:79]
	v_mfma_f32_16x16x32_bf16 v[4:7], v[136:139], v[242:245], v[4:7]
	v_mfma_f32_16x16x32_bf16 v[12:15], v[140:143], v[242:245], v[12:15]
	global_load_dwordx4 v[128:131], v[248:249], off
	global_load_dwordx4 v[132:135], v[248:249], off offset:256
	global_load_dwordx4 v[136:139], v[250:251], off
	global_load_dwordx4 v[140:143], v[250:251], off offset:256
	s_waitcnt lgkmcnt(0)
	s_barrier
	s_add_i32 s9, s8, 3
	s_min_u32 s10, s9, 87
	s_lshl_b32 s96, s10, 13
	v_lshl_add_u64 v[174:175], v[188:189], 0, s[96:97]
	global_load_dwordx4 v[168:171], v[174:175], off offset:-2048
	global_load_dwordx4 v[172:175], v[174:175], off offset:2048
	ds_read_b128 v[196:199], v246 offset:8192
	ds_read_b128 v[200:203], v246 offset:9216
	ds_read_b128 v[204:207], v246 offset:10240
	ds_read_b128 v[242:245], v246 offset:11264
	s_lshl_b32 s96, s10, 11
	v_lshl_add_u64 v[248:249], v[184:185], 0, s[96:97]
	v_lshl_add_u64 v[250:251], v[186:187], 0, s[96:97]
	s_waitcnt vmcnt(8) lgkmcnt(3)
	v_mfma_f32_16x16x32_bf16 v[112:115], v[144:147], v[196:199], v[112:115]
	v_mfma_f32_16x16x32_bf16 v[120:123], v[148:151], v[196:199], v[120:123]
	v_mfma_f32_16x16x32_bf16 v[48:51], v[152:155], v[196:199], v[48:51]
	v_mfma_f32_16x16x32_bf16 v[56:59], v[156:159], v[196:199], v[56:59]
	ds_read_b128 v[196:199], v246 offset:12288
	s_waitcnt lgkmcnt(3)
	v_mfma_f32_16x16x32_bf16 v[116:119], v[144:147], v[200:203], v[116:119]
	v_mfma_f32_16x16x32_bf16 v[124:127], v[148:151], v[200:203], v[124:127]
	v_mfma_f32_16x16x32_bf16 v[52:55], v[152:155], v[200:203], v[52:55]
	v_mfma_f32_16x16x32_bf16 v[60:63], v[156:159], v[200:203], v[60:63]
	ds_read_b128 v[200:203], v246 offset:13312
	s_waitcnt lgkmcnt(3)
	v_mfma_f32_16x16x32_bf16 v[96:99], v[144:147], v[204:207], v[96:99]
	v_mfma_f32_16x16x32_bf16 v[104:107], v[148:151], v[204:207], v[104:107]
	v_mfma_f32_16x16x32_bf16 v[32:35], v[152:155], v[204:207], v[32:35]
	v_mfma_f32_16x16x32_bf16 v[40:43], v[156:159], v[204:207], v[40:43]
	ds_read_b128 v[204:207], v246 offset:14336
	s_waitcnt lgkmcnt(3)
	v_mfma_f32_16x16x32_bf16 v[100:103], v[144:147], v[242:245], v[100:103]
	v_mfma_f32_16x16x32_bf16 v[108:111], v[148:151], v[242:245], v[108:111]
	v_mfma_f32_16x16x32_bf16 v[36:39], v[152:155], v[242:245], v[36:39]
	v_mfma_f32_16x16x32_bf16 v[44:47], v[156:159], v[242:245], v[44:47]
	ds_read_b128 v[242:245], v246 offset:15360
	s_waitcnt vmcnt(6)
	ds_write_b128 v241, v[160:163] offset:0
	ds_write_b128 v241, v[164:167] offset:4096
	s_waitcnt lgkmcnt(5)
	v_mfma_f32_16x16x32_bf16 v[80:83], v[144:147], v[196:199], v[80:83]
	v_mfma_f32_16x16x32_bf16 v[88:91], v[148:151], v[196:199], v[88:91]
	v_mfma_f32_16x16x32_bf16 v[16:19], v[152:155], v[196:199], v[16:19]
	v_mfma_f32_16x16x32_bf16 v[24:27], v[156:159], v[196:199], v[24:27]
	s_waitcnt lgkmcnt(4)
	v_mfma_f32_16x16x32_bf16 v[84:87], v[144:147], v[200:203], v[84:87]
	v_mfma_f32_16x16x32_bf16 v[92:95], v[148:151], v[200:203], v[92:95]
	v_mfma_f32_16x16x32_bf16 v[20:23], v[152:155], v[200:203], v[20:23]
	v_mfma_f32_16x16x32_bf16 v[28:31], v[156:159], v[200:203], v[28:31]
	s_waitcnt lgkmcnt(3)
	v_mfma_f32_16x16x32_bf16 v[64:67], v[144:147], v[204:207], v[64:67]
	v_mfma_f32_16x16x32_bf16 v[72:75], v[148:151], v[204:207], v[72:75]
	v_mfma_f32_16x16x32_bf16 v[0:3], v[152:155], v[204:207], v[0:3]
	v_mfma_f32_16x16x32_bf16 v[8:11], v[156:159], v[204:207], v[8:11]
	s_waitcnt lgkmcnt(2)
	v_mfma_f32_16x16x32_bf16 v[68:71], v[144:147], v[242:245], v[68:71]
	v_mfma_f32_16x16x32_bf16 v[76:79], v[148:151], v[242:245], v[76:79]
	v_mfma_f32_16x16x32_bf16 v[4:7], v[152:155], v[242:245], v[4:7]
	v_mfma_f32_16x16x32_bf16 v[12:15], v[156:159], v[242:245], v[12:15]
	global_load_dwordx4 v[144:147], v[248:249], off
	global_load_dwordx4 v[148:151], v[248:249], off offset:256
	global_load_dwordx4 v[152:155], v[250:251], off
	global_load_dwordx4 v[156:159], v[250:251], off offset:256
	s_add_i32 s8, s8, 2
	s_cmp_lt_u32 s8, 88
	s_waitcnt lgkmcnt(0)
	s_barrier
	s_cbranch_scc1 .Lg16_down_k
	s_nop 7
	v_permlane16_swap_b32_e32 v112, v116
	v_permlane16_swap_b32_e32 v113, v117
	v_permlane16_swap_b32_e32 v114, v118
	v_permlane16_swap_b32_e32 v115, v119
	v_permlane16_swap_b32_e32 v120, v124
	v_permlane16_swap_b32_e32 v121, v125
	v_permlane16_swap_b32_e32 v122, v126
	v_permlane16_swap_b32_e32 v123, v127
	v_permlane16_swap_b32_e32 v96, v100
	v_permlane16_swap_b32_e32 v97, v101
	v_permlane16_swap_b32_e32 v98, v102
	v_permlane16_swap_b32_e32 v99, v103
	v_permlane16_swap_b32_e32 v104, v108
	v_permlane16_swap_b32_e32 v105, v109
	v_permlane16_swap_b32_e32 v106, v110
	v_permlane16_swap_b32_e32 v107, v111
	v_permlane16_swap_b32_e32 v80, v84
	v_permlane16_swap_b32_e32 v81, v85
	v_permlane16_swap_b32_e32 v82, v86
	v_permlane16_swap_b32_e32 v83, v87
	v_permlane16_swap_b32_e32 v88, v92
	v_permlane16_swap_b32_e32 v89, v93
	v_permlane16_swap_b32_e32 v90, v94
	v_permlane16_swap_b32_e32 v91, v95
	v_permlane16_swap_b32_e32 v64, v68
	v_permlane16_swap_b32_e32 v65, v69
	v_permlane16_swap_b32_e32 v66, v70
	v_permlane16_swap_b32_e32 v67, v71
	v_permlane16_swap_b32_e32 v72, v76
	v_permlane16_swap_b32_e32 v73, v77
	v_permlane16_swap_b32_e32 v74, v78
	v_permlane16_swap_b32_e32 v75, v79
	v_permlane16_swap_b32_e32 v48, v52
	v_permlane16_swap_b32_e32 v49, v53
	v_permlane16_swap_b32_e32 v50, v54
	v_permlane16_swap_b32_e32 v51, v55
	v_permlane16_swap_b32_e32 v56, v60
	v_permlane16_swap_b32_e32 v57, v61
	v_permlane16_swap_b32_e32 v58, v62
	v_permlane16_swap_b32_e32 v59, v63
	v_permlane16_swap_b32_e32 v32, v36
	v_permlane16_swap_b32_e32 v33, v37
	v_permlane16_swap_b32_e32 v34, v38
	v_permlane16_swap_b32_e32 v35, v39
	v_permlane16_swap_b32_e32 v40, v44
	v_permlane16_swap_b32_e32 v41, v45
	v_permlane16_swap_b32_e32 v42, v46
	v_permlane16_swap_b32_e32 v43, v47
	v_permlane16_swap_b32_e32 v16, v20
	v_permlane16_swap_b32_e32 v17, v21
	v_permlane16_swap_b32_e32 v18, v22
	v_permlane16_swap_b32_e32 v19, v23
	v_permlane16_swap_b32_e32 v24, v28
	v_permlane16_swap_b32_e32 v25, v29
	v_permlane16_swap_b32_e32 v26, v30
	v_permlane16_swap_b32_e32 v27, v31
	v_permlane16_swap_b32_e32 v0, v4
	v_permlane16_swap_b32_e32 v1, v5
	v_permlane16_swap_b32_e32 v2, v6
	v_permlane16_swap_b32_e32 v3, v7
	v_permlane16_swap_b32_e32 v8, v12
	v_permlane16_swap_b32_e32 v9, v13
	v_permlane16_swap_b32_e32 v10, v14
	v_permlane16_swap_b32_e32 v11, v15
	v_permlane32_swap_b32_e32 v112, v116
	v_permlane32_swap_b32_e32 v113, v117
	v_permlane32_swap_b32_e32 v114, v118
	v_permlane32_swap_b32_e32 v115, v119
	v_permlane32_swap_b32_e32 v120, v124
	v_permlane32_swap_b32_e32 v121, v125
	v_permlane32_swap_b32_e32 v122, v126
	v_permlane32_swap_b32_e32 v123, v127
	v_permlane32_swap_b32_e32 v96, v100
	v_permlane32_swap_b32_e32 v97, v101
	v_permlane32_swap_b32_e32 v98, v102
	v_permlane32_swap_b32_e32 v99, v103
	v_permlane32_swap_b32_e32 v104, v108
	v_permlane32_swap_b32_e32 v105, v109
	v_permlane32_swap_b32_e32 v106, v110
	v_permlane32_swap_b32_e32 v107, v111
	v_permlane32_swap_b32_e32 v80, v84
	v_permlane32_swap_b32_e32 v81, v85
	v_permlane32_swap_b32_e32 v82, v86
	v_permlane32_swap_b32_e32 v83, v87
	v_permlane32_swap_b32_e32 v88, v92
	v_permlane32_swap_b32_e32 v89, v93
	v_permlane32_swap_b32_e32 v90, v94
	v_permlane32_swap_b32_e32 v91, v95
	v_permlane32_swap_b32_e32 v64, v68
	v_permlane32_swap_b32_e32 v65, v69
	v_permlane32_swap_b32_e32 v66, v70
	v_permlane32_swap_b32_e32 v67, v71
	v_permlane32_swap_b32_e32 v72, v76
	v_permlane32_swap_b32_e32 v73, v77
	v_permlane32_swap_b32_e32 v74, v78
	v_permlane32_swap_b32_e32 v75, v79
	v_permlane32_swap_b32_e32 v48, v52
	v_permlane32_swap_b32_e32 v49, v53
	v_permlane32_swap_b32_e32 v50, v54
	v_permlane32_swap_b32_e32 v51, v55
	v_permlane32_swap_b32_e32 v56, v60
	v_permlane32_swap_b32_e32 v57, v61
	v_permlane32_swap_b32_e32 v58, v62
	v_permlane32_swap_b32_e32 v59, v63
	v_permlane32_swap_b32_e32 v32, v36
	v_permlane32_swap_b32_e32 v33, v37
	v_permlane32_swap_b32_e32 v34, v38
	v_permlane32_swap_b32_e32 v35, v39
	v_permlane32_swap_b32_e32 v40, v44
	v_permlane32_swap_b32_e32 v41, v45
	v_permlane32_swap_b32_e32 v42, v46
	v_permlane32_swap_b32_e32 v43, v47
	v_permlane32_swap_b32_e32 v16, v20
	v_permlane32_swap_b32_e32 v17, v21
	v_permlane32_swap_b32_e32 v18, v22
	v_permlane32_swap_b32_e32 v19, v23
	v_permlane32_swap_b32_e32 v24, v28
	v_permlane32_swap_b32_e32 v25, v29
	v_permlane32_swap_b32_e32 v26, v30
	v_permlane32_swap_b32_e32 v27, v31
	v_permlane32_swap_b32_e32 v0, v4
	v_permlane32_swap_b32_e32 v1, v5
	v_permlane32_swap_b32_e32 v2, v6
	v_permlane32_swap_b32_e32 v3, v7
	v_permlane32_swap_b32_e32 v8, v12
	v_permlane32_swap_b32_e32 v9, v13
	v_permlane32_swap_b32_e32 v10, v14
	v_permlane32_swap_b32_e32 v11, v15
	s_waitcnt vmcnt(0)
	s_movk_i32 s8, 0x2400
	s_waitcnt vmcnt(0)
	v_and_b32_e32 v132, 0xffffffc0, v181
	v_mul_lo_u32 v129, v237, s8
	v_lshlrev_b32_e32 v130, 2, v238
	v_lshl_add_u32 v156, s7, 8, v132
	v_mul_u32_u24_e32 v132, 0x110, v183
	v_or_b32_e32 v131, v129, v130
	v_lshlrev_b32_e32 v132, 2, v132
	v_add_u32_e32 v131, v131, v132
	v_add3_u32 v132, v129, v132, v130
	v_readlane_b32 s8, v253, 36
	v_lshlrev_b32_e32 v128, 2, v181
	v_add_u32_e32 v133, 0x800, v131
	v_add_u32_e32 v134, 0x800, v132
	v_lshrrev_b32_e32 v155, 4, v239
	v_readlane_b32 s12, v253, 40
	v_readlane_b32 s13, v253, 41
	v_readlane_b32 s14, v253, 42
	v_readlane_b32 s15, v253, 43
	v_readlane_b32 s16, v253, 44
	v_readlane_b32 s17, v253, 45
	v_readlane_b32 s18, v253, 46
	v_readlane_b32 s19, v253, 47
	v_and_b32_e32 v128, 60, v128
	ds_write2_b32 v131, v112, v113 offset1:68
	ds_write2_b32 v132, v96, v97 offset0:32 offset1:100
	ds_write2_b32 v131, v114, v115 offset0:136 offset1:204
	ds_write2_b32 v132, v98, v99 offset0:168 offset1:236
	ds_write2_b32 v133, v116, v117 offset0:32 offset1:100
	ds_write2_b32 v134, v100, v101 offset0:64 offset1:132
	ds_write2_b32 v133, v118, v119 offset0:168 offset1:236
	v_or_b32_e32 v100, v156, v155
	v_readlane_b32 s20, v253, 48
	v_readlane_b32 s21, v253, 49
	v_readlane_b32 s22, v253, 50
	v_readlane_b32 s23, v253, 51
	s_mov_b64 s[12:13], s[16:17]
	v_lshl_or_b32 v144, v128, 2, v129
	v_lshl_or_b32 v128, s6, 7, v128
	s_movk_i32 s6, 0x110
	v_cmp_gt_i32_e32 vcc, s39, v100
	v_add_u32_e32 v96, 0xffff8000, v100
	v_ashrrev_i32_e32 v97, 31, v100
	s_mov_b64 s[14:15], s[18:19]
	v_mad_u32_u24 v130, v155, s6, v144
	v_cndmask_b32_e32 v97, 0, v97, vcc
	v_cndmask_b32_e32 v96, v96, v100, vcc
	v_mov_b32_e32 v144, s63
	v_mov_b32_e32 v145, s15
	v_mov_b32_e32 v146, s62
	v_mov_b32_e32 v147, s14
	v_min_i32_e32 v100, 0x8000, v100
	v_add_u32_e32 v135, 0xa00, v132
	v_add_u32_e32 v136, 0x1000, v131
	v_add_u32_e32 v137, 0x1000, v132
	v_add_u32_e32 v138, 0x1200, v131
	v_add_u32_e32 v139, 0x1200, v132
	v_add_u32_e32 v140, 0x1800, v131
	v_add_u32_e32 v141, 0x1800, v132
	v_add_u32_e32 v142, 0x1a00, v131
	v_add_u32_e32 v143, 0x1c00, v132
	v_ashrrev_i32_e32 v129, 31, v128
	v_cndmask_b32_e32 v99, v144, v145, vcc
	v_cndmask_b32_e32 v98, v146, v147, vcc
	v_lshlrev_b64 v[96:97], 12, v[96:97]
	v_ashrrev_i32_e32 v100, 12, v100
	ds_write2_b32 v135, v102, v103 offset0:72 offset1:140
	ds_write2_b32 v136, v120, v121 offset0:64 offset1:132
	ds_write2_b32 v137, v104, v105 offset0:96 offset1:164
	ds_write2_b32 v138, v122, v123 offset0:72 offset1:140
	ds_write2_b32 v139, v106, v107 offset0:104 offset1:172
	ds_write2_b32 v140, v124, v125 offset0:96 offset1:164
	ds_write2_b32 v141, v108, v109 offset0:128 offset1:196
	ds_write2_b32 v142, v126, v127 offset0:104 offset1:172
	ds_write2_b32 v143, v110, v111 offset0:8 offset1:76
	v_lshl_add_u64 v[98:99], v[98:99], 0, v[96:97]
	v_lshlrev_b64 v[96:97], 2, v[128:129]
	v_mul_hi_i32_i24_e32 v101, 0x6000, v100
	v_mul_i32_i24_e32 v100, 0x6000, v100
	s_waitcnt lgkmcnt(0)
	v_lshl_add_u64 v[98:99], v[98:99], 0, v[96:97]
	v_lshl_add_u64 v[100:101], s[0:1], 0, v[100:101]
	v_lshl_add_u64 v[100:101], v[100:101], 0, v[96:97]
	ds_read_b128 v[102:105], v130
	global_load_dwordx4 v[106:109], v[98:99], off
	global_load_dwordx4 v[110:113], v[100:101], off
	v_or_b32_e32 v148, 4, v155
	v_or_b32_e32 v149, 8, v155
	v_or_b32_e32 v150, 12, v155
	v_or_b32_e32 v151, 16, v155
	v_or_b32_e32 v152, 20, v155
	v_or_b32_e32 v153, 24, v155
	v_or_b32_e32 v154, 28, v155
	v_or_b32_e32 v157, v156, v154
	v_readlane_b32 s6, v254, 11
	s_add_i32 s2, s2, s6
	s_cmp_lt_i32 s2, s26
	v_readlane_b32 s9, v253, 37
	v_readlane_b32 s10, v253, 38
	v_readlane_b32 s11, v253, 39
	s_mov_b64 s[16:17], s[20:21]
	s_mov_b64 s[18:19], s[22:23]
	s_waitcnt vmcnt(0) lgkmcnt(0)
	v_pk_fma_f32 v[102:103], v[102:103], v[110:111], v[106:107]
	v_pk_fma_f32 v[104:105], v[104:105], v[112:113], v[108:109]
	v_or_b32_e32 v106, v156, v148
	global_store_dwordx4 v[98:99], v[102:105], off
	v_cmp_gt_i32_e32 vcc, s39, v106
	s_nop 0
	v_ashrrev_i32_e32 v102, 31, v106
	v_add_u32_e32 v104, 0xffff8000, v106
	v_cndmask_b32_e32 v103, 0, v102, vcc
	v_cndmask_b32_e32 v102, v104, v106, vcc
	v_cndmask_b32_e32 v105, v144, v145, vcc
	v_cndmask_b32_e32 v104, v146, v147, vcc
	v_lshlrev_b64 v[102:103], 12, v[102:103]
	v_lshl_add_u64 v[102:103], v[104:105], 0, v[102:103]
	v_min_i32_e32 v104, 0x8000, v106
	v_ashrrev_i32_e32 v104, 12, v104
	v_mul_hi_i32_i24_e32 v105, 0x6000, v104
	v_mul_i32_i24_e32 v104, 0x6000, v104
	v_lshl_add_u64 v[102:103], v[102:103], 0, v[96:97]
	v_lshl_add_u64 v[104:105], s[0:1], 0, v[104:105]
	v_lshl_add_u64 v[104:105], v[104:105], 0, v[96:97]
	ds_read_b128 v[106:109], v130 offset:1088
	global_load_dwordx4 v[110:113], v[102:103], off
	global_load_dwordx4 v[114:117], v[104:105], off
	s_waitcnt vmcnt(0) lgkmcnt(0)
	v_pk_fma_f32 v[106:107], v[106:107], v[114:115], v[110:111]
	v_pk_fma_f32 v[108:109], v[108:109], v[116:117], v[112:113]
	v_or_b32_e32 v110, v156, v149
	global_store_dwordx4 v[102:103], v[106:109], off
	v_cmp_gt_i32_e32 vcc, s39, v110
	s_nop 0
	v_ashrrev_i32_e32 v106, 31, v110
	v_add_u32_e32 v108, 0xffff8000, v110
	v_cndmask_b32_e32 v107, 0, v106, vcc
	v_cndmask_b32_e32 v106, v108, v110, vcc
	v_cndmask_b32_e32 v109, v144, v145, vcc
	v_cndmask_b32_e32 v108, v146, v147, vcc
	v_lshlrev_b64 v[106:107], 12, v[106:107]
	v_lshl_add_u64 v[106:107], v[108:109], 0, v[106:107]
	v_min_i32_e32 v108, 0x8000, v110
	v_ashrrev_i32_e32 v108, 12, v108
	v_mul_hi_i32_i24_e32 v109, 0x6000, v108
	v_mul_i32_i24_e32 v108, 0x6000, v108
	v_lshl_add_u64 v[106:107], v[106:107], 0, v[96:97]
	v_lshl_add_u64 v[108:109], s[0:1], 0, v[108:109]
	v_lshl_add_u64 v[108:109], v[108:109], 0, v[96:97]
	ds_read_b128 v[110:113], v130 offset:2176
	global_load_dwordx4 v[114:117], v[106:107], off
	global_load_dwordx4 v[118:121], v[108:109], off
	s_waitcnt vmcnt(0) lgkmcnt(0)
	v_pk_fma_f32 v[110:111], v[110:111], v[118:119], v[114:115]
	v_pk_fma_f32 v[112:113], v[112:113], v[120:121], v[116:117]
	v_or_b32_e32 v114, v156, v150
	global_store_dwordx4 v[106:107], v[110:113], off
	v_cmp_gt_i32_e32 vcc, s39, v114
	s_nop 0
	v_ashrrev_i32_e32 v110, 31, v114
	v_add_u32_e32 v112, 0xffff8000, v114
	v_cndmask_b32_e32 v111, 0, v110, vcc
	v_cndmask_b32_e32 v110, v112, v114, vcc
	v_cndmask_b32_e32 v113, v144, v145, vcc
	v_cndmask_b32_e32 v112, v146, v147, vcc
	v_lshlrev_b64 v[110:111], 12, v[110:111]
	v_lshl_add_u64 v[110:111], v[112:113], 0, v[110:111]
	v_min_i32_e32 v112, 0x8000, v114
	v_ashrrev_i32_e32 v112, 12, v112
	v_mul_hi_i32_i24_e32 v113, 0x6000, v112
	v_mul_i32_i24_e32 v112, 0x6000, v112
	v_lshl_add_u64 v[110:111], v[110:111], 0, v[96:97]
	v_lshl_add_u64 v[112:113], s[0:1], 0, v[112:113]
	v_lshl_add_u64 v[112:113], v[112:113], 0, v[96:97]
	ds_read_b128 v[114:117], v130 offset:3264
	global_load_dwordx4 v[118:121], v[110:111], off
	global_load_dwordx4 v[122:125], v[112:113], off
	s_waitcnt vmcnt(0) lgkmcnt(0)
	v_pk_fma_f32 v[114:115], v[114:115], v[122:123], v[118:119]
	v_pk_fma_f32 v[116:117], v[116:117], v[124:125], v[120:121]
	v_or_b32_e32 v118, v156, v151
	global_store_dwordx4 v[110:111], v[114:117], off
	v_cmp_gt_i32_e32 vcc, s39, v118
	s_nop 0
	v_ashrrev_i32_e32 v114, 31, v118
	v_add_u32_e32 v116, 0xffff8000, v118
	v_cndmask_b32_e32 v115, 0, v114, vcc
	v_cndmask_b32_e32 v114, v116, v118, vcc
	v_cndmask_b32_e32 v117, v144, v145, vcc
	v_cndmask_b32_e32 v116, v146, v147, vcc
	v_lshlrev_b64 v[114:115], 12, v[114:115]
	v_lshl_add_u64 v[114:115], v[116:117], 0, v[114:115]
	v_min_i32_e32 v116, 0x8000, v118
	v_ashrrev_i32_e32 v116, 12, v116
	v_mul_hi_i32_i24_e32 v117, 0x6000, v116
	v_mul_i32_i24_e32 v116, 0x6000, v116
	v_lshl_add_u64 v[114:115], v[114:115], 0, v[96:97]
	v_lshl_add_u64 v[116:117], s[0:1], 0, v[116:117]
	v_lshl_add_u64 v[116:117], v[116:117], 0, v[96:97]
	ds_read_b128 v[118:121], v130 offset:4352
	global_load_dwordx4 v[122:125], v[114:115], off
	global_load_dwordx4 v[126:129], v[116:117], off
	s_waitcnt vmcnt(0) lgkmcnt(0)
	v_pk_fma_f32 v[118:119], v[118:119], v[126:127], v[122:123]
	v_pk_fma_f32 v[120:121], v[120:121], v[128:129], v[124:125]
	v_or_b32_e32 v122, v156, v152
	global_store_dwordx4 v[114:115], v[118:121], off
	v_cmp_gt_i32_e32 vcc, s39, v122
	s_nop 0
	v_ashrrev_i32_e32 v118, 31, v122
	v_add_u32_e32 v120, 0xffff8000, v122
	v_cndmask_b32_e32 v119, 0, v118, vcc
	v_cndmask_b32_e32 v118, v120, v122, vcc
	v_cndmask_b32_e32 v121, v144, v145, vcc
	v_cndmask_b32_e32 v120, v146, v147, vcc
	v_lshlrev_b64 v[118:119], 12, v[118:119]
	v_lshl_add_u64 v[118:119], v[120:121], 0, v[118:119]
	v_min_i32_e32 v120, 0x8000, v122
	v_ashrrev_i32_e32 v120, 12, v120
	v_mul_hi_i32_i24_e32 v121, 0x6000, v120
	v_mul_i32_i24_e32 v120, 0x6000, v120
	v_lshl_add_u64 v[118:119], v[118:119], 0, v[96:97]
	v_lshl_add_u64 v[120:121], s[0:1], 0, v[120:121]
	v_lshl_add_u64 v[120:121], v[120:121], 0, v[96:97]
	ds_read_b128 v[122:125], v130 offset:5440
	global_load_dwordx4 v[126:129], v[118:119], off
	global_load_dwordx4 v[158:161], v[120:121], off
	s_waitcnt vmcnt(0) lgkmcnt(0)
	v_pk_fma_f32 v[122:123], v[122:123], v[158:159], v[126:127]
	v_pk_fma_f32 v[124:125], v[124:125], v[160:161], v[128:129]
	v_or_b32_e32 v126, v156, v153
	global_store_dwordx4 v[118:119], v[122:125], off
	v_cmp_gt_i32_e32 vcc, s39, v126
	s_nop 0
	v_ashrrev_i32_e32 v122, 31, v126
	v_add_u32_e32 v124, 0xffff8000, v126
	v_cndmask_b32_e32 v123, 0, v122, vcc
	v_cndmask_b32_e32 v122, v124, v126, vcc
	v_cndmask_b32_e32 v125, v144, v145, vcc
	v_cndmask_b32_e32 v124, v146, v147, vcc
	v_lshlrev_b64 v[122:123], 12, v[122:123]
	v_lshl_add_u64 v[122:123], v[124:125], 0, v[122:123]
	v_min_i32_e32 v124, 0x8000, v126
	v_ashrrev_i32_e32 v124, 12, v124
	v_mul_hi_i32_i24_e32 v125, 0x6000, v124
	v_mul_i32_i24_e32 v124, 0x6000, v124
	v_lshl_add_u64 v[122:123], v[122:123], 0, v[96:97]
	v_lshl_add_u64 v[124:125], s[0:1], 0, v[124:125]
	v_lshl_add_u64 v[124:125], v[124:125], 0, v[96:97]
	ds_read_b128 v[126:129], v130 offset:6528
	global_load_dwordx4 v[158:161], v[122:123], off
	global_load_dwordx4 v[162:165], v[124:125], off
	v_cmp_gt_i32_e32 vcc, s39, v157
	s_waitcnt vmcnt(0) lgkmcnt(0)
	v_pk_fma_f32 v[126:127], v[126:127], v[162:163], v[158:159]
	v_pk_fma_f32 v[128:129], v[128:129], v[164:165], v[160:161]
	global_store_dwordx4 v[122:123], v[126:129], off
	ds_read_b128 v[158:161], v130 offset:7616
	s_nop 0
	v_ashrrev_i32_e32 v126, 31, v157
	v_add_u32_e32 v128, 0xffff8000, v157
	v_cndmask_b32_e32 v127, 0, v126, vcc
	v_cndmask_b32_e32 v126, v128, v157, vcc
	v_cndmask_b32_e32 v129, v144, v145, vcc
	v_cndmask_b32_e32 v128, v146, v147, vcc
	v_lshlrev_b64 v[126:127], 12, v[126:127]
	v_lshl_add_u64 v[126:127], v[128:129], 0, v[126:127]
	v_min_i32_e32 v128, 0x8000, v157
	v_ashrrev_i32_e32 v128, 12, v128
	v_mul_hi_i32_i24_e32 v129, 0x6000, v128
	v_mul_i32_i24_e32 v128, 0x6000, v128
	v_lshl_add_u64 v[126:127], v[126:127], 0, v[96:97]
	v_lshl_add_u64 v[128:129], s[0:1], 0, v[128:129]
	v_lshl_add_u64 v[128:129], v[128:129], 0, v[96:97]
	global_load_dwordx4 v[162:165], v[126:127], off
	global_load_dwordx4 v[166:169], v[128:129], off
	s_waitcnt vmcnt(0) lgkmcnt(0)
	v_pk_fma_f32 v[158:159], v[158:159], v[166:167], v[162:163]
	v_pk_fma_f32 v[160:161], v[160:161], v[168:169], v[164:165]
	global_store_dwordx4 v[126:127], v[158:161], off
	s_waitcnt lgkmcnt(0)
	ds_write2_b32 v131, v80, v81 offset1:68
	ds_write2_b32 v132, v64, v65 offset0:32 offset1:100
	ds_write2_b32 v131, v82, v83 offset0:136 offset1:204
	ds_write2_b32 v132, v66, v67 offset0:168 offset1:236
	ds_write2_b32 v133, v84, v85 offset0:32 offset1:100
	ds_write2_b32 v134, v68, v69 offset0:64 offset1:132
	ds_write2_b32 v133, v86, v87 offset0:168 offset1:236
	ds_write2_b32 v135, v70, v71 offset0:72 offset1:140
	ds_write2_b32 v136, v88, v89 offset0:64 offset1:132
	ds_write2_b32 v137, v72, v73 offset0:96 offset1:164
	ds_write2_b32 v138, v90, v91 offset0:72 offset1:140
	ds_write2_b32 v139, v74, v75 offset0:104 offset1:172
	ds_write2_b32 v140, v92, v93 offset0:96 offset1:164
	ds_write2_b32 v141, v76, v77 offset0:128 offset1:196
	ds_write2_b32 v142, v94, v95 offset0:104 offset1:172
	ds_write2_b32 v143, v78, v79 offset0:8 offset1:76
	s_waitcnt lgkmcnt(0)
	ds_read_b128 v[64:67], v130
	global_load_dwordx4 v[68:71], v[98:99], off offset:256
	global_load_dwordx4 v[72:75], v[100:101], off offset:256
	s_waitcnt vmcnt(0) lgkmcnt(0)
	v_pk_fma_f32 v[64:65], v[64:65], v[72:73], v[68:69]
	v_pk_fma_f32 v[66:67], v[66:67], v[74:75], v[70:71]
	global_store_dwordx4 v[98:99], v[64:67], off offset:256
	ds_read_b128 v[64:67], v130 offset:1088
	global_load_dwordx4 v[68:71], v[102:103], off offset:256
	global_load_dwordx4 v[72:75], v[104:105], off offset:256
	s_waitcnt vmcnt(0) lgkmcnt(0)
	v_pk_fma_f32 v[64:65], v[64:65], v[72:73], v[68:69]
	v_pk_fma_f32 v[66:67], v[66:67], v[74:75], v[70:71]
	global_store_dwordx4 v[102:103], v[64:67], off offset:256
	ds_read_b128 v[64:67], v130 offset:2176
	global_load_dwordx4 v[68:71], v[106:107], off offset:256
	global_load_dwordx4 v[72:75], v[108:109], off offset:256
	s_waitcnt vmcnt(0) lgkmcnt(0)
	v_pk_fma_f32 v[64:65], v[64:65], v[72:73], v[68:69]
	v_pk_fma_f32 v[66:67], v[66:67], v[74:75], v[70:71]
	global_store_dwordx4 v[106:107], v[64:67], off offset:256
	ds_read_b128 v[64:67], v130 offset:3264
	global_load_dwordx4 v[68:71], v[110:111], off offset:256
	global_load_dwordx4 v[72:75], v[112:113], off offset:256
	s_waitcnt vmcnt(0) lgkmcnt(0)
	v_pk_fma_f32 v[64:65], v[64:65], v[72:73], v[68:69]
	v_pk_fma_f32 v[66:67], v[66:67], v[74:75], v[70:71]
	global_store_dwordx4 v[110:111], v[64:67], off offset:256
	ds_read_b128 v[64:67], v130 offset:4352
	global_load_dwordx4 v[68:71], v[114:115], off offset:256
	global_load_dwordx4 v[72:75], v[116:117], off offset:256
	s_waitcnt vmcnt(0) lgkmcnt(0)
	v_pk_fma_f32 v[64:65], v[64:65], v[72:73], v[68:69]
	v_pk_fma_f32 v[66:67], v[66:67], v[74:75], v[70:71]
	global_store_dwordx4 v[114:115], v[64:67], off offset:256
	ds_read_b128 v[64:67], v130 offset:5440
	global_load_dwordx4 v[68:71], v[118:119], off offset:256
	global_load_dwordx4 v[72:75], v[120:121], off offset:256
	s_waitcnt vmcnt(0) lgkmcnt(0)
	v_pk_fma_f32 v[64:65], v[64:65], v[72:73], v[68:69]
	v_pk_fma_f32 v[66:67], v[66:67], v[74:75], v[70:71]
	global_store_dwordx4 v[118:119], v[64:67], off offset:256
	ds_read_b128 v[64:67], v130 offset:6528
	global_load_dwordx4 v[68:71], v[122:123], off offset:256
	global_load_dwordx4 v[72:75], v[124:125], off offset:256
	s_waitcnt vmcnt(0) lgkmcnt(0)
	v_pk_fma_f32 v[64:65], v[64:65], v[72:73], v[68:69]
	v_pk_fma_f32 v[66:67], v[66:67], v[74:75], v[70:71]
	global_store_dwordx4 v[122:123], v[64:67], off offset:256
	ds_read_b128 v[64:67], v130 offset:7616
	global_load_dwordx4 v[68:71], v[126:127], off offset:256
	global_load_dwordx4 v[72:75], v[128:129], off offset:256
	s_waitcnt vmcnt(0) lgkmcnt(0)
	v_pk_fma_f32 v[64:65], v[64:65], v[72:73], v[68:69]
	v_pk_fma_f32 v[66:67], v[66:67], v[74:75], v[70:71]
	global_store_dwordx4 v[126:127], v[64:67], off offset:256
	s_waitcnt lgkmcnt(0)
	ds_write2_b32 v131, v48, v49 offset1:68
	ds_write2_b32 v132, v32, v33 offset0:32 offset1:100
	ds_write2_b32 v131, v50, v51 offset0:136 offset1:204
	ds_write2_b32 v132, v34, v35 offset0:168 offset1:236
	ds_write2_b32 v133, v52, v53 offset0:32 offset1:100
	ds_write2_b32 v134, v36, v37 offset0:64 offset1:132
	ds_write2_b32 v133, v54, v55 offset0:168 offset1:236
	ds_write2_b32 v135, v38, v39 offset0:72 offset1:140
	ds_write2_b32 v136, v56, v57 offset0:64 offset1:132
	ds_write2_b32 v137, v40, v41 offset0:96 offset1:164
	ds_write2_b32 v138, v58, v59 offset0:72 offset1:140
	ds_write2_b32 v139, v42, v43 offset0:104 offset1:172
	ds_write2_b32 v140, v60, v61 offset0:96 offset1:164
	ds_write2_b32 v141, v44, v45 offset0:128 offset1:196
	ds_write2_b32 v142, v62, v63 offset0:104 offset1:172
	ds_write2_b32 v143, v46, v47 offset0:8 offset1:76
	v_or_b32_e32 v64, 32, v156
	v_or_b32_e32 v36, v64, v155
	v_cmp_gt_i32_e32 vcc, s39, v36
	v_ashrrev_i32_e32 v32, 31, v36
	v_add_u32_e32 v34, 0xffff8000, v36
	v_cndmask_b32_e32 v33, 0, v32, vcc
	v_cndmask_b32_e32 v32, v34, v36, vcc
	v_cndmask_b32_e32 v35, v144, v145, vcc
	v_cndmask_b32_e32 v34, v146, v147, vcc
	v_lshlrev_b64 v[32:33], 12, v[32:33]
	v_lshl_add_u64 v[32:33], v[34:35], 0, v[32:33]
	v_min_i32_e32 v34, 0x8000, v36
	v_ashrrev_i32_e32 v34, 12, v34
	v_mul_hi_i32_i24_e32 v35, 0x6000, v34
	v_mul_i32_i24_e32 v34, 0x6000, v34
	s_waitcnt lgkmcnt(0)
	v_lshl_add_u64 v[32:33], v[32:33], 0, v[96:97]
	v_lshl_add_u64 v[34:35], s[0:1], 0, v[34:35]
	v_lshl_add_u64 v[34:35], v[34:35], 0, v[96:97]
	ds_read_b128 v[36:39], v130
	global_load_dwordx4 v[40:43], v[32:33], off
	global_load_dwordx4 v[44:47], v[34:35], off
	s_waitcnt vmcnt(0) lgkmcnt(0)
	v_pk_fma_f32 v[36:37], v[36:37], v[44:45], v[40:41]
	v_pk_fma_f32 v[38:39], v[38:39], v[46:47], v[42:43]
	v_or_b32_e32 v40, v64, v148
	global_store_dwordx4 v[32:33], v[36:39], off
	v_cmp_gt_i32_e32 vcc, s39, v40
	s_nop 0
	v_ashrrev_i32_e32 v36, 31, v40
	v_add_u32_e32 v38, 0xffff8000, v40
	v_cndmask_b32_e32 v37, 0, v36, vcc
	v_cndmask_b32_e32 v36, v38, v40, vcc
	v_cndmask_b32_e32 v39, v144, v145, vcc
	v_cndmask_b32_e32 v38, v146, v147, vcc
	v_lshlrev_b64 v[36:37], 12, v[36:37]
	v_lshl_add_u64 v[36:37], v[38:39], 0, v[36:37]
	v_min_i32_e32 v38, 0x8000, v40
	v_ashrrev_i32_e32 v38, 12, v38
	v_mul_hi_i32_i24_e32 v39, 0x6000, v38
	v_mul_i32_i24_e32 v38, 0x6000, v38
	v_lshl_add_u64 v[36:37], v[36:37], 0, v[96:97]
	v_lshl_add_u64 v[38:39], s[0:1], 0, v[38:39]
	v_lshl_add_u64 v[38:39], v[38:39], 0, v[96:97]
	ds_read_b128 v[40:43], v130 offset:1088
	global_load_dwordx4 v[44:47], v[36:37], off
	global_load_dwordx4 v[48:51], v[38:39], off
	s_waitcnt vmcnt(0) lgkmcnt(0)
	v_pk_fma_f32 v[40:41], v[40:41], v[48:49], v[44:45]
	v_pk_fma_f32 v[42:43], v[42:43], v[50:51], v[46:47]
	v_or_b32_e32 v44, v64, v149
	global_store_dwordx4 v[36:37], v[40:43], off
	v_cmp_gt_i32_e32 vcc, s39, v44
	s_nop 0
	v_ashrrev_i32_e32 v40, 31, v44
	v_add_u32_e32 v42, 0xffff8000, v44
	v_cndmask_b32_e32 v41, 0, v40, vcc
	v_cndmask_b32_e32 v40, v42, v44, vcc
	v_cndmask_b32_e32 v43, v144, v145, vcc
	v_cndmask_b32_e32 v42, v146, v147, vcc
	v_lshlrev_b64 v[40:41], 12, v[40:41]
	v_lshl_add_u64 v[40:41], v[42:43], 0, v[40:41]
	v_min_i32_e32 v42, 0x8000, v44
	v_ashrrev_i32_e32 v42, 12, v42
	v_mul_hi_i32_i24_e32 v43, 0x6000, v42
	v_mul_i32_i24_e32 v42, 0x6000, v42
	v_lshl_add_u64 v[40:41], v[40:41], 0, v[96:97]
	v_lshl_add_u64 v[42:43], s[0:1], 0, v[42:43]
	v_lshl_add_u64 v[42:43], v[42:43], 0, v[96:97]
	ds_read_b128 v[44:47], v130 offset:2176
	global_load_dwordx4 v[48:51], v[40:41], off
	global_load_dwordx4 v[52:55], v[42:43], off
	s_waitcnt vmcnt(0) lgkmcnt(0)
	v_pk_fma_f32 v[44:45], v[44:45], v[52:53], v[48:49]
	v_pk_fma_f32 v[46:47], v[46:47], v[54:55], v[50:51]
	v_or_b32_e32 v48, v64, v150
	global_store_dwordx4 v[40:41], v[44:47], off
	v_cmp_gt_i32_e32 vcc, s39, v48
	s_nop 0
	v_ashrrev_i32_e32 v44, 31, v48
	v_add_u32_e32 v46, 0xffff8000, v48
	v_cndmask_b32_e32 v45, 0, v44, vcc
	v_cndmask_b32_e32 v44, v46, v48, vcc
	v_cndmask_b32_e32 v47, v144, v145, vcc
	v_cndmask_b32_e32 v46, v146, v147, vcc
	v_lshlrev_b64 v[44:45], 12, v[44:45]
	v_lshl_add_u64 v[44:45], v[46:47], 0, v[44:45]
	v_min_i32_e32 v46, 0x8000, v48
	v_ashrrev_i32_e32 v46, 12, v46
	v_mul_hi_i32_i24_e32 v47, 0x6000, v46
	v_mul_i32_i24_e32 v46, 0x6000, v46
	v_lshl_add_u64 v[44:45], v[44:45], 0, v[96:97]
	v_lshl_add_u64 v[46:47], s[0:1], 0, v[46:47]
	v_lshl_add_u64 v[46:47], v[46:47], 0, v[96:97]
	ds_read_b128 v[48:51], v130 offset:3264
	global_load_dwordx4 v[52:55], v[44:45], off
	global_load_dwordx4 v[56:59], v[46:47], off
	s_waitcnt vmcnt(0) lgkmcnt(0)
	v_pk_fma_f32 v[48:49], v[48:49], v[56:57], v[52:53]
	v_pk_fma_f32 v[50:51], v[50:51], v[58:59], v[54:55]
	v_or_b32_e32 v52, v64, v151
	global_store_dwordx4 v[44:45], v[48:51], off
	v_cmp_gt_i32_e32 vcc, s39, v52
	s_nop 0
	v_ashrrev_i32_e32 v48, 31, v52
	v_add_u32_e32 v50, 0xffff8000, v52
	v_cndmask_b32_e32 v49, 0, v48, vcc
	v_cndmask_b32_e32 v48, v50, v52, vcc
	v_cndmask_b32_e32 v51, v144, v145, vcc
	v_cndmask_b32_e32 v50, v146, v147, vcc
	v_lshlrev_b64 v[48:49], 12, v[48:49]
	v_lshl_add_u64 v[48:49], v[50:51], 0, v[48:49]
	v_min_i32_e32 v50, 0x8000, v52
	v_ashrrev_i32_e32 v50, 12, v50
	v_mul_hi_i32_i24_e32 v51, 0x6000, v50
	v_mul_i32_i24_e32 v50, 0x6000, v50
	v_lshl_add_u64 v[48:49], v[48:49], 0, v[96:97]
	v_lshl_add_u64 v[50:51], s[0:1], 0, v[50:51]
	v_lshl_add_u64 v[50:51], v[50:51], 0, v[96:97]
	ds_read_b128 v[52:55], v130 offset:4352
	global_load_dwordx4 v[56:59], v[48:49], off
	global_load_dwordx4 v[60:63], v[50:51], off
	s_waitcnt vmcnt(0) lgkmcnt(0)
	v_pk_fma_f32 v[52:53], v[52:53], v[60:61], v[56:57]
	v_pk_fma_f32 v[54:55], v[54:55], v[62:63], v[58:59]
	v_or_b32_e32 v56, v64, v152
	global_store_dwordx4 v[48:49], v[52:55], off
	v_cmp_gt_i32_e32 vcc, s39, v56
	s_nop 0
	v_ashrrev_i32_e32 v52, 31, v56
	v_add_u32_e32 v54, 0xffff8000, v56
	v_cndmask_b32_e32 v53, 0, v52, vcc
	v_cndmask_b32_e32 v52, v54, v56, vcc
	v_cndmask_b32_e32 v55, v144, v145, vcc
	v_cndmask_b32_e32 v54, v146, v147, vcc
	v_lshlrev_b64 v[52:53], 12, v[52:53]
	v_lshl_add_u64 v[52:53], v[54:55], 0, v[52:53]
	v_min_i32_e32 v54, 0x8000, v56
	v_ashrrev_i32_e32 v54, 12, v54
	v_mul_hi_i32_i24_e32 v55, 0x6000, v54
	v_mul_i32_i24_e32 v54, 0x6000, v54
	v_lshl_add_u64 v[52:53], v[52:53], 0, v[96:97]
	v_lshl_add_u64 v[54:55], s[0:1], 0, v[54:55]
	v_lshl_add_u64 v[54:55], v[54:55], 0, v[96:97]
	ds_read_b128 v[56:59], v130 offset:5440
	global_load_dwordx4 v[60:63], v[52:53], off
	global_load_dwordx4 v[66:69], v[54:55], off
	s_waitcnt vmcnt(0) lgkmcnt(0)
	v_pk_fma_f32 v[56:57], v[56:57], v[66:67], v[60:61]
	v_pk_fma_f32 v[58:59], v[58:59], v[68:69], v[62:63]
	v_or_b32_e32 v60, v64, v153
	global_store_dwordx4 v[52:53], v[56:59], off
	v_cmp_gt_i32_e32 vcc, s39, v60
	v_or_b32_e32 v64, v64, v154
	v_ashrrev_i32_e32 v56, 31, v60
	v_add_u32_e32 v58, 0xffff8000, v60
	v_cndmask_b32_e32 v57, 0, v56, vcc
	v_cndmask_b32_e32 v56, v58, v60, vcc
	v_cndmask_b32_e32 v59, v144, v145, vcc
	v_cndmask_b32_e32 v58, v146, v147, vcc
	v_lshlrev_b64 v[56:57], 12, v[56:57]
	v_lshl_add_u64 v[56:57], v[58:59], 0, v[56:57]
	v_min_i32_e32 v58, 0x8000, v60
	v_ashrrev_i32_e32 v58, 12, v58
	v_mul_hi_i32_i24_e32 v59, 0x6000, v58
	v_mul_i32_i24_e32 v58, 0x6000, v58
	v_lshl_add_u64 v[56:57], v[56:57], 0, v[96:97]
	v_lshl_add_u64 v[58:59], s[0:1], 0, v[58:59]
	v_lshl_add_u64 v[58:59], v[58:59], 0, v[96:97]
	ds_read_b128 v[60:63], v130 offset:6528
	global_load_dwordx4 v[66:69], v[56:57], off
	global_load_dwordx4 v[70:73], v[58:59], off
	v_cmp_gt_i32_e32 vcc, s39, v64
	s_waitcnt vmcnt(0) lgkmcnt(0)
	v_pk_fma_f32 v[60:61], v[60:61], v[70:71], v[66:67]
	v_pk_fma_f32 v[62:63], v[62:63], v[72:73], v[68:69]
	global_store_dwordx4 v[56:57], v[60:63], off
	s_nop 1
	v_ashrrev_i32_e32 v60, 31, v64
	v_add_u32_e32 v62, 0xffff8000, v64
	v_cndmask_b32_e32 v61, 0, v60, vcc
	v_cndmask_b32_e32 v60, v62, v64, vcc
	v_cndmask_b32_e32 v63, v144, v145, vcc
	v_cndmask_b32_e32 v62, v146, v147, vcc
	v_lshlrev_b64 v[60:61], 12, v[60:61]
	v_lshl_add_u64 v[60:61], v[62:63], 0, v[60:61]
	v_min_i32_e32 v62, 0x8000, v64
	v_ashrrev_i32_e32 v62, 12, v62
	v_mul_hi_i32_i24_e32 v63, 0x6000, v62
	v_mul_i32_i24_e32 v62, 0x6000, v62
	v_lshl_add_u64 v[60:61], v[60:61], 0, v[96:97]
	v_lshl_add_u64 v[62:63], s[0:1], 0, v[62:63]
	v_lshl_add_u64 v[62:63], v[62:63], 0, v[96:97]
	ds_read_b128 v[64:67], v130 offset:7616
	global_load_dwordx4 v[68:71], v[60:61], off
	global_load_dwordx4 v[72:75], v[62:63], off
	s_waitcnt vmcnt(0) lgkmcnt(0)
	v_pk_fma_f32 v[64:65], v[64:65], v[72:73], v[68:69]
	v_pk_fma_f32 v[66:67], v[66:67], v[74:75], v[70:71]
	global_store_dwordx4 v[60:61], v[64:67], off
	s_waitcnt lgkmcnt(0)
	ds_write2_b32 v131, v16, v17 offset1:68
	ds_write2_b32 v132, v0, v1 offset0:32 offset1:100
	ds_write2_b32 v131, v18, v19 offset0:136 offset1:204
	ds_write2_b32 v132, v2, v3 offset0:168 offset1:236
	ds_write2_b32 v133, v20, v21 offset0:32 offset1:100
	ds_write2_b32 v134, v4, v5 offset0:64 offset1:132
	ds_write2_b32 v133, v22, v23 offset0:168 offset1:236
	ds_write2_b32 v135, v6, v7 offset0:72 offset1:140
	ds_write2_b32 v136, v24, v25 offset0:64 offset1:132
	ds_write2_b32 v137, v8, v9 offset0:96 offset1:164
	ds_write2_b32 v138, v26, v27 offset0:72 offset1:140
	ds_write2_b32 v139, v10, v11 offset0:104 offset1:172
	ds_write2_b32 v140, v28, v29 offset0:96 offset1:164
	ds_write2_b32 v141, v12, v13 offset0:128 offset1:196
	ds_write2_b32 v142, v30, v31 offset0:104 offset1:172
	ds_write2_b32 v143, v14, v15 offset0:8 offset1:76
	s_waitcnt lgkmcnt(0)
	ds_read_b128 v[0:3], v130
	global_load_dwordx4 v[4:7], v[32:33], off offset:256
	global_load_dwordx4 v[8:11], v[34:35], off offset:256
	s_waitcnt vmcnt(0) lgkmcnt(0)
	v_pk_fma_f32 v[0:1], v[0:1], v[8:9], v[4:5]
	v_pk_fma_f32 v[2:3], v[2:3], v[10:11], v[6:7]
	global_store_dwordx4 v[32:33], v[0:3], off offset:256
	ds_read_b128 v[0:3], v130 offset:1088
	global_load_dwordx4 v[4:7], v[36:37], off offset:256
	global_load_dwordx4 v[8:11], v[38:39], off offset:256
	s_waitcnt vmcnt(0) lgkmcnt(0)
	v_pk_fma_f32 v[0:1], v[0:1], v[8:9], v[4:5]
	v_pk_fma_f32 v[2:3], v[2:3], v[10:11], v[6:7]
	global_store_dwordx4 v[36:37], v[0:3], off offset:256
	ds_read_b128 v[0:3], v130 offset:2176
	global_load_dwordx4 v[4:7], v[40:41], off offset:256
	global_load_dwordx4 v[8:11], v[42:43], off offset:256
	s_waitcnt vmcnt(0) lgkmcnt(0)
	v_pk_fma_f32 v[0:1], v[0:1], v[8:9], v[4:5]
	v_pk_fma_f32 v[2:3], v[2:3], v[10:11], v[6:7]
	global_store_dwordx4 v[40:41], v[0:3], off offset:256
	ds_read_b128 v[0:3], v130 offset:3264
	global_load_dwordx4 v[4:7], v[44:45], off offset:256
	global_load_dwordx4 v[8:11], v[46:47], off offset:256
	s_waitcnt vmcnt(0) lgkmcnt(0)
	v_pk_fma_f32 v[0:1], v[0:1], v[8:9], v[4:5]
	v_pk_fma_f32 v[2:3], v[2:3], v[10:11], v[6:7]
	global_store_dwordx4 v[44:45], v[0:3], off offset:256
	ds_read_b128 v[0:3], v130 offset:4352
	global_load_dwordx4 v[4:7], v[48:49], off offset:256
	global_load_dwordx4 v[8:11], v[50:51], off offset:256
	s_waitcnt vmcnt(0) lgkmcnt(0)
	v_pk_fma_f32 v[0:1], v[0:1], v[8:9], v[4:5]
	v_pk_fma_f32 v[2:3], v[2:3], v[10:11], v[6:7]
	global_store_dwordx4 v[48:49], v[0:3], off offset:256
	ds_read_b128 v[0:3], v130 offset:5440
	global_load_dwordx4 v[4:7], v[52:53], off offset:256
	global_load_dwordx4 v[8:11], v[54:55], off offset:256
	s_waitcnt vmcnt(0) lgkmcnt(0)
	v_pk_fma_f32 v[0:1], v[0:1], v[8:9], v[4:5]
	v_pk_fma_f32 v[2:3], v[2:3], v[10:11], v[6:7]
	global_store_dwordx4 v[52:53], v[0:3], off offset:256
	ds_read_b128 v[0:3], v130 offset:6528
	global_load_dwordx4 v[4:7], v[56:57], off offset:256
	global_load_dwordx4 v[8:11], v[58:59], off offset:256
	s_waitcnt vmcnt(0) lgkmcnt(0)
	v_pk_fma_f32 v[0:1], v[0:1], v[8:9], v[4:5]
	v_pk_fma_f32 v[2:3], v[2:3], v[10:11], v[6:7]
	global_store_dwordx4 v[56:57], v[0:3], off offset:256
	ds_read_b128 v[0:3], v130 offset:7616
	global_load_dwordx4 v[4:7], v[60:61], off offset:256
	global_load_dwordx4 v[8:11], v[62:63], off offset:256
	s_waitcnt vmcnt(0) lgkmcnt(0)
	v_pk_fma_f32 v[0:1], v[0:1], v[8:9], v[4:5]
	v_pk_fma_f32 v[2:3], v[2:3], v[10:11], v[6:7]
	global_store_dwordx4 v[60:61], v[0:3], off offset:256
	s_waitcnt lgkmcnt(0)
	s_barrier
	s_cbranch_scc1 .LBB0_1086
